# attention: all K fragments loaded up front in distinct registers (one LDS wait instead of four per tile)
# baseline (speedup 1.0000x reference)
; #define LAS __attribute__((address_space(3)))
; template <bool BAND>
; __device__ __forceinline__ void tile_body(f32x16* o, float& l_reg, const bf16x8* qr, const LAS unsigned char* kbs, const LAS float* wb, int vb, float ci, int hi, int keybase, int qabs) {
;     ...
; #pragma unroll
;     for (int g4 = 0; g4 < 4; ++g4) {
;         const f32x4 ba = *(const LAS f32x4*)(wb + 8 * g4 + 4 * hi) + ci, bb = *(const LAS f32x4*)(wb + 32 + 8 * g4 + 4 * hi) + ci;
; #pragma unroll
;         for (int e = 0; e < 4; ++e) { p0[4 * g4 + e] = ba[e]; p1[4 * g4 + e] = bb[e]; }
;     }
; #pragma unroll
;     for (int d0 = 0; d0 < 4; ++d0) {
;         const bf16x8 b0 = *(const LAS bf16x8*)(kbs + d0 * 2048), b1 = *(const LAS bf16x8*)(kbs + d0 * 2048 + 512);
;         p0 = __builtin_amdgcn_mfma_f32_32x32x16_bf16(b0, qr[d0], p0, 0, 0, 0); p1 = __builtin_amdgcn_mfma_f32_32x32x16_bf16(b1, qr[d0], p1, 0, 0, 0); }
;     if (BAND) {
; #pragma unroll
;         for (int r = 0; r < 16; ++r) { const int key = keybase + 8 * (r >> 2) + (r & 3); if (key > qabs) p0[r] = -INFINITY; if (key + 32 > qabs) p1[r] = -INFINITY; }
.LBB0_783:
	s_andn2_saveexec_b64 s[12:13], s[12:13]
	v_mov_b32_e32 v149, s67
	v_add_f32_e32 v149, s28, v149
	v_add_f32_e32 v149, s66, v149
	s_or_b64 exec, exec, s[12:13]
	v_add_f32_e32 v149, v0, v149
	s_xor_b32 s74, s70, 1
	v_add_f32_e32 v0, v150, v149
	s_lshl_b32 s12, s74, 8
	v_sub_f32_e32 v0, v0, v140
	s_add_i32 s71, s53, s12
	s_lshl_b32 s78, s74, 14
	s_max_i32 s12, s48, 4
	v_mul_f32_e32 v140, 0x3fb8aa3b, v0
	v_lshl_add_u32 v0, v137, 2, s71
	v_readfirstlane_b32 s76, v149
	v_add_u32_e32 v149, s78, v143
	s_add_i32 s28, s12, -4
	ds_write_b32 v0, v140 offset:32768
	ds_write_b128 v149, v[66:69]
	ds_write_b128 v149, v[74:77] offset:8192
	s_lshl_b64 s[12:13], s[28:29], 11
	s_waitcnt lgkmcnt(0)
	v_lshl_add_u64 v[66:67], v[110:111], 0, s[12:13]
	s_lshl_b64 s[12:13], s[28:29], 16
	global_load_dword v140, v[66:67], off
	v_lshl_add_u64 v[74:75], v[106:107], 0, s[12:13]
	global_load_dwordx4 v[66:69], v[74:75], off
	v_cndmask_b32_e64 v74, 0, 1, s[58:59]
	v_lshl_add_u64 v[152:153], v[108:109], 0, s[12:13]
	v_cmp_ne_u32_e64 s[12:13], 1, v74
	global_load_dwordx4 v[74:77], v[152:153], off
	s_andn2_b64 vcc, exec, s[58:59]
	s_cbranch_vccnz .LBB0_792
	s_and_b64 vcc, exec, s[98:99]
	s_cbranch_vccnz .LBB0_792
	s_sub_i32 s28, s75, 64
	s_cmp_gt_i32 s28, s73
	s_cbranch_scc1 .LBB0_792
	s_lshl_b32 s64, s70, 8
	s_lshl_b32 s28, s70, 14
	s_add_i32 s66, s53, s64
	s_cmp_lt_i32 s48, s72
	v_add_u32_e32 v151, s28, v144
	s_mov_b64 s[64:65], -1
	v_add_u32_e32 v152, s28, v145
	v_lshl_add_u32 v153, v142, 2, s66
	s_cbranch_scc1 .LBB0_789
	ds_read_b128 v[34:37], v153 offset:32768
	ds_read_b128 v[38:41], v153 offset:32800
	ds_read_b128 v[42:45], v153 offset:32832
	ds_read_b128 v[46:49], v153 offset:32864
	ds_read_b128 v[50:53], v153 offset:32896
	ds_read_b128 v[54:57], v153 offset:32928
	ds_read_b128 v[58:61], v153 offset:32960
	ds_read_b128 v[62:65], v153 offset:32992
	ds_read_b128 v[154:157], v152
	ds_read_b128 v[158:161], v152 offset:512
	s_waitcnt lgkmcnt(4)
	ds_read_b128 v[210:213], v152 offset:2048
	ds_read_b128 v[214:217], v152 offset:2560
	ds_read_b128 v[218:221], v152 offset:4096
	ds_read_b128 v[222:225], v152 offset:4608
	ds_read_b128 v[226:229], v152 offset:6656
	ds_read_b128 v[230:233], v152 offset:6144
	v_pk_add_f32 v[56:57], v[118:119], v[56:57]
	s_waitcnt lgkmcnt(9)
	v_pk_add_f32 v[60:61], v[122:123], v[60:61]
	s_waitcnt lgkmcnt(8)
	v_pk_add_f32 v[64:65], v[126:127], v[64:65]
	v_pk_add_f32 v[52:53], v[114:115], v[52:53]
	v_pk_add_f32 v[62:63], v[124:125], v[62:63]
	v_pk_add_f32 v[58:59], v[120:121], v[58:59]
	v_pk_add_f32 v[54:55], v[116:117], v[54:55]
	v_pk_add_f32 v[50:51], v[112:113], v[50:51]
	v_pk_add_f32 v[48:49], v[126:127], v[48:49]
	v_pk_add_f32 v[44:45], v[122:123], v[44:45]
	v_pk_add_f32 v[40:41], v[118:119], v[40:41]
	v_pk_add_f32 v[36:37], v[114:115], v[36:37]
	v_pk_add_f32 v[46:47], v[124:125], v[46:47]
	v_pk_add_f32 v[42:43], v[120:121], v[42:43]
	v_pk_add_f32 v[38:39], v[116:117], v[38:39]
	v_pk_add_f32 v[34:35], v[112:113], v[34:35]
	s_waitcnt lgkmcnt(6)
	v_mfma_f32_32x32x16_bf16 v[50:65], v[158:161], v[94:97], v[50:65]
	v_mfma_f32_32x32x16_bf16 v[34:49], v[154:157], v[94:97], v[34:49]
	s_waitcnt lgkmcnt(4)
	v_mfma_f32_32x32x16_bf16 v[50:65], v[214:217], v[98:101], v[50:65]
	v_mfma_f32_32x32x16_bf16 v[34:49], v[210:213], v[98:101], v[34:49]
	s_waitcnt lgkmcnt(2)
	v_mfma_f32_32x32x16_bf16 v[50:65], v[222:225], v[102:105], v[50:65]
	v_mfma_f32_32x32x16_bf16 v[34:49], v[218:221], v[102:105], v[34:49]
	s_waitcnt lgkmcnt(1)
	v_mfma_f32_32x32x16_bf16 v[50:65], v[226:229], v[90:93], v[50:65]
	v_add_u32_e32 v154, s75, v142
	v_subrev_u32_e32 v156, 32, v154
	v_subrev_u32_e32 v155, 64, v154
	v_cmp_le_i32_e32 vcc, v156, v147
	s_waitcnt lgkmcnt(0)
	v_mfma_f32_32x32x16_bf16 v[34:49], v[230:233], v[90:93], v[34:49]
	s_nop 5
	v_cndmask_b32_e32 v50, v134, v50, vcc
	v_cmp_lt_i32_e32 vcc, v155, v147
	s_nop 3
	v_cndmask_b32_e32 v35, v134, v35, vcc
	v_cmp_le_i32_e32 vcc, v155, v147
	v_subrev_u32_e32 v155, 31, v154
	v_exp_f32_e32 v35, v35
	v_cndmask_b32_e32 v34, v134, v34, vcc
	v_cmp_le_i32_e32 vcc, v155, v147
	v_subrev_u32_e32 v155, 62, v154
	v_exp_f32_e32 v34, v34
	v_cndmask_b32_e32 v51, v134, v51, vcc
	v_cmp_le_i32_e32 vcc, v155, v147
	s_nop 1
	v_cndmask_b32_e32 v155, v134, v36, vcc
	v_subrev_u32_e32 v36, 30, v154
	v_cmp_le_i32_e32 vcc, v36, v147
	v_subrev_u32_e32 v36, 61, v154
	s_nop 0
	v_cndmask_b32_e32 v52, v134, v52, vcc
	v_cmp_le_i32_e32 vcc, v36, v147
	v_subrev_u32_e32 v36, 29, v154
	s_nop 0
	v_cndmask_b32_e32 v156, v134, v37, vcc
	v_cmp_le_i32_e32 vcc, v36, v147
	v_subrev_u32_e32 v36, 56, v154
	v_exp_f32_e32 v37, v51
	v_cndmask_b32_e32 v53, v134, v53, vcc
	v_cmp_le_i32_e32 vcc, v36, v147
	v_subrev_u32_e32 v36, 24, v154
	s_nop 0
	v_cndmask_b32_e32 v157, v134, v38, vcc
	v_cmp_le_i32_e32 vcc, v36, v147
	v_subrev_u32_e32 v36, 55, v154
	v_exp_f32_e32 v38, v155
	v_cndmask_b32_e32 v54, v134, v54, vcc
	v_cmp_le_i32_e32 vcc, v36, v147
	v_subrev_u32_e32 v36, 23, v154
	s_nop 0
	v_cndmask_b32_e32 v158, v134, v39, vcc
	v_cmp_le_i32_e32 vcc, v36, v147
	v_subrev_u32_e32 v36, 54, v154
	v_exp_f32_e32 v39, v156
	v_cndmask_b32_e32 v55, v134, v55, vcc
	v_cmp_le_i32_e32 vcc, v36, v147
	v_subrev_u32_e32 v36, 22, v154
	v_cvt_pk_bf16_f32 v156, v34, v35
	v_cndmask_b32_e32 v159, v134, v40, vcc
	v_cmp_le_i32_e32 vcc, v36, v147
	v_subrev_u32_e32 v36, 53, v154
	v_exp_f32_e32 v40, v52
	v_cndmask_b32_e32 v56, v134, v56, vcc
	v_cmp_le_i32_e32 vcc, v36, v147
	v_subrev_u32_e32 v36, 21, v154
	s_nop 0
	v_cndmask_b32_e32 v160, v134, v41, vcc
	v_cmp_le_i32_e32 vcc, v36, v147
	v_subrev_u32_e32 v36, 48, v154
	v_exp_f32_e32 v41, v53
	v_cndmask_b32_e32 v57, v134, v57, vcc
	v_cmp_le_i32_e32 vcc, v36, v147
; __device__ __forceinline__ void pv(f32x16* o, int vb, bf16x8 pa0, bf16x8 pa1, bf16x8 pa2, bf16x8 pa3) {
; #pragma unroll
;     for (int d0 = 0; d0 < 2; ++d0) { s16x4 lo[4], hi[4];
; #pragma unroll
;         for (int ks = 0; ks < 4; ++ks) {
;             asm volatile("ds_read_b64_tr_b16 %0,%1 offset:%c2" : "=&v"(lo[ks]) : "v"(vb), "i"(d0 * 4096 + ks * 1024) : "memory");
;             asm volatile("ds_read_b64_tr_b16 %0,%1 offset:%c2" : "=&v"(hi[ks]) : "v"(vb), "i"(d0 * 4096 + ks * 1024 + 512) : "memory"); }
;         asm volatile("s_waitcnt lgkmcnt(0)" ::: "memory"); __builtin_amdgcn_sched_barrier(0);
;     ...
;         o[d0] = __builtin_amdgcn_mfma_f32_32x32x16_bf16(pa0, PK(0), o[d0], 0, 0, 0);
;         o[d0] = __builtin_amdgcn_mfma_f32_32x32x16_bf16(pa1, PK(1), o[d0], 0, 0, 0);
;         o[d0] = __builtin_amdgcn_mfma_f32_32x32x16_bf16(pa2, PK(2), o[d0], 0, 0, 0);
;         o[d0] = __builtin_amdgcn_mfma_f32_32x32x16_bf16(pa3, PK(3), o[d0], 0, 0, 0);
; template <bool BAND>
; __device__ __forceinline__ void tile_body(f32x16* o, float& l_reg, const bf16x8* qr, const LAS unsigned char* kbs, const LAS float* wb, int vb, float ci, int hi, int keybase, int qabs) {
;     ...
;         for (int r = 0; r < 16; ++r) { const int key = keybase + 8 * (r >> 2) + (r & 3); if (key > qabs) p0[r] = -INFINITY; if (key + 32 > qabs) p1[r] = -INFINITY; }
;     }
;     f32x2 s2 = {0.f, 0.f};
; #pragma unroll
;     for (int r = 0; r < 16; r += 2) {
;         p0[r] = __builtin_amdgcn_exp2f(p0[r]); p0[r + 1] = __builtin_amdgcn_exp2f(p0[r + 1]); p1[r] = __builtin_amdgcn_exp2f(p1[r]); p1[r + 1] = __builtin_amdgcn_exp2f(p1[r + 1]);
;         s2 += (f32x2){p0[r], p0[r + 1]}; s2 += (f32x2){p1[r], p1[r + 1]}; }
;     l_reg += s2.x + s2.y;
;     u32x4 pw0, pw1, pw2, pw3;
;     pw0 = (u32x4){cvtpk(p0[0], p0[1]), cvtpk(p0[2], p0[3]), cvtpk(p0[4], p0[5]), cvtpk(p0[6], p0[7])};
;     pw1 = (u32x4){cvtpk(p0[8], p0[9]), cvtpk(p0[10], p0[11]), cvtpk(p0[12], p0[13]), cvtpk(p0[14], p0[15])};
;     pw2 = (u32x4){cvtpk(p1[0], p1[1]), cvtpk(p1[2], p1[3]), cvtpk(p1[4], p1[5]), cvtpk(p1[6], p1[7])};
;     pw3 = (u32x4){cvtpk(p1[8], p1[9]), cvtpk(p1[10], p1[11]), cvtpk(p1[12], p1[13]), cvtpk(p1[14], p1[15])};
;     pv(o, vb, __builtin_bit_cast(bf16x8, pw0), __builtin_bit_cast(bf16x8, pw1), __builtin_bit_cast(bf16x8, pw2), __builtin_bit_cast(bf16x8, pw3));
	v_add_u32_e32 v36, -16, v154
	v_exp_f32_e32 v51, v57
	v_cndmask_b32_e32 v161, v134, v42, vcc
	v_cmp_le_i32_e32 vcc, v36, v147
	v_subrev_u32_e32 v36, 47, v154
	v_exp_f32_e32 v52, v161
	v_cndmask_b32_e32 v58, v134, v58, vcc
	v_cmp_le_i32_e32 vcc, v36, v147
	v_add_u32_e32 v36, -15, v154
	s_nop 0
	v_cndmask_b32_e32 v162, v134, v43, vcc
	v_cmp_le_i32_e32 vcc, v36, v147
	v_subrev_u32_e32 v36, 46, v154
	v_pk_add_f32 v[42:43], v[34:35], 0 op_sel_hi:[1,0]
	v_cndmask_b32_e32 v59, v134, v59, vcc
	v_cmp_le_i32_e32 vcc, v36, v147
	v_add_u32_e32 v36, -14, v154
	v_exp_f32_e32 v53, v162
	v_cndmask_b32_e32 v163, v134, v44, vcc
	v_cmp_le_i32_e32 vcc, v36, v147
	v_subrev_u32_e32 v36, 45, v154
	v_exp_f32_e32 v44, v157
	v_cndmask_b32_e32 v60, v134, v60, vcc
	v_cmp_le_i32_e32 vcc, v36, v147
	v_add_u32_e32 v36, -13, v154
	v_cvt_pk_bf16_f32 v157, v38, v39
	v_cndmask_b32_e32 v164, v134, v45, vcc
	v_cmp_le_i32_e32 vcc, v36, v147
	v_subrev_u32_e32 v36, 40, v154
	v_exp_f32_e32 v45, v158
	v_cndmask_b32_e32 v61, v134, v61, vcc
	v_cmp_le_i32_e32 vcc, v36, v147
	v_add_u32_e32 v36, -8, v154
	v_exp_f32_e32 v57, v164
	v_cndmask_b32_e32 v165, v134, v46, vcc
	v_cmp_le_i32_e32 vcc, v36, v147
	v_subrev_u32_e32 v36, 39, v154
	v_exp_f32_e32 v46, v54
	v_cndmask_b32_e32 v62, v134, v62, vcc
	v_cmp_le_i32_e32 vcc, v36, v147
	v_add_u32_e32 v36, -7, v154
	v_exp_f32_e32 v54, v58
	v_cndmask_b32_e32 v166, v134, v47, vcc
	v_cmp_le_i32_e32 vcc, v36, v147
	v_subrev_u32_e32 v36, 38, v154
	v_exp_f32_e32 v47, v55
	v_cndmask_b32_e32 v63, v134, v63, vcc
	v_cmp_le_i32_e32 vcc, v36, v147
	v_add_u32_e32 v36, -6, v154
	v_exp_f32_e32 v55, v59
	v_cndmask_b32_e32 v167, v134, v48, vcc
	v_cmp_le_i32_e32 vcc, v36, v147
	v_subrev_u32_e32 v36, 37, v154
	v_exp_f32_e32 v48, v159
	v_cndmask_b32_e32 v168, v134, v64, vcc
	v_cmp_le_i32_e32 vcc, v36, v147
	v_add_u32_e32 v36, -5, v154
	v_exp_f32_e32 v58, v60
	v_cndmask_b32_e32 v169, v134, v49, vcc
	v_cmp_le_i32_e32 vcc, v36, v147
	v_exp_f32_e32 v36, v50
	v_exp_f32_e32 v49, v160
	v_exp_f32_e32 v50, v56
	v_exp_f32_e32 v56, v163
	v_pk_add_f32 v[42:43], v[36:37], v[42:43]
	v_exp_f32_e32 v59, v61
	v_pk_add_f32 v[42:43], v[38:39], v[42:43]
	v_exp_f32_e32 v64, v167
	v_pk_add_f32 v[42:43], v[40:41], v[42:43]
	v_cvt_pk_bf16_f32 v167, v50, v51
	v_pk_add_f32 v[42:43], v[44:45], v[42:43]
	v_exp_f32_e32 v60, v165
	v_pk_add_f32 v[42:43], v[46:47], v[42:43]
	v_exp_f32_e32 v61, v166
	v_pk_add_f32 v[42:43], v[48:49], v[42:43]
	v_cvt_pk_bf16_f32 v160, v52, v53
	v_pk_add_f32 v[42:43], v[50:51], v[42:43]
	ds_read_b64_tr_b16 v[50:51],v151 offset:0
	v_exp_f32_e32 v62, v62
	v_pk_add_f32 v[42:43], v[52:53], v[42:43]
	ds_read_b64_tr_b16 v[52:53],v151 offset:512
	v_exp_f32_e32 v63, v63
	v_pk_add_f32 v[42:43], v[54:55], v[42:43]
	v_exp_f32_e32 v172, v168
	v_cvt_pk_bf16_f32 v168, v54, v55
	ds_read_b64_tr_b16 v[54:55],v151 offset:1024
	v_cndmask_b32_e32 v154, v134, v65, vcc
	v_pk_add_f32 v[42:43], v[56:57], v[42:43]
	v_exp_f32_e32 v65, v169
	v_cvt_pk_bf16_f32 v161, v56, v57
	ds_read_b64_tr_b16 v[56:57],v151 offset:1536
	v_pk_add_f32 v[42:43], v[58:59], v[42:43]
	v_exp_f32_e32 v173, v154
	v_cvt_pk_bf16_f32 v169, v58, v59
	ds_read_b64_tr_b16 v[58:59],v151 offset:2048
	v_pk_add_f32 v[42:43], v[60:61], v[42:43]
	v_cvt_pk_bf16_f32 v162, v60, v61
	ds_read_b64_tr_b16 v[60:61],v151 offset:2560
	v_pk_add_f32 v[42:43], v[62:63], v[42:43]
	v_cvt_pk_bf16_f32 v170, v62, v63
	ds_read_b64_tr_b16 v[62:63],v151 offset:3072
	v_pk_add_f32 v[42:43], v[64:65], v[42:43]
	v_cvt_pk_bf16_f32 v163, v64, v65
	ds_read_b64_tr_b16 v[64:65],v151 offset:3584
	v_pk_add_f32 v[42:43], v[172:173], v[42:43]
	s_waitcnt lgkmcnt(0)
	v_cvt_pk_bf16_f32 v158, v44, v45
	v_add_f32_e32 v42, v42, v43
	v_add_f32_e32 v154, v148, v42
	v_cvt_pk_bf16_f32 v159, v48, v49
	v_cvt_pk_bf16_f32 v164, v36, v37
	v_cvt_pk_bf16_f32 v165, v40, v41
	v_cvt_pk_bf16_f32 v166, v46, v47
	v_cvt_pk_bf16_f32 v171, v172, v173
	v_mfma_f32_32x32x16_bf16 v[2:17], v[156:159], v[50:53], v[2:17]
	ds_read_b64_tr_b16 v[172:173],v151 offset:4096
	ds_read_b64_tr_b16 v[174:175],v151 offset:4608
	ds_read_b64_tr_b16 v[176:177],v151 offset:5120
	ds_read_b64_tr_b16 v[178:179],v151 offset:5632
	ds_read_b64_tr_b16 v[180:181],v151 offset:6144
	ds_read_b64_tr_b16 v[182:183],v151 offset:6656
	ds_read_b64_tr_b16 v[184:185],v151 offset:7168
	v_mfma_f32_32x32x16_bf16 v[2:17], v[160:163], v[54:57], v[2:17]
	ds_read_b64_tr_b16 v[186:187],v151 offset:7680
	s_waitcnt lgkmcnt(0)
	v_mfma_f32_32x32x16_bf16 v[2:17], v[164:167], v[58:61], v[2:17]
	v_mfma_f32_32x32x16_bf16 v[2:17], v[168:171], v[62:65], v[2:17]
	v_mfma_f32_32x32x16_bf16 v[18:33], v[156:159], v[172:175], v[18:33]
	s_mov_b64 s[64:65], 0
	v_mfma_f32_32x32x16_bf16 v[18:33], v[160:163], v[176:179], v[18:33]
	v_mfma_f32_32x32x16_bf16 v[18:33], v[164:167], v[180:183], v[18:33]
	v_mfma_f32_32x32x16_bf16 v[18:33], v[168:171], v[184:187], v[18:33]
; #define LAS __attribute__((address_space(3)))
; __device__ __forceinline__ void pv(f32x16* o, int vb, bf16x8 pa0, bf16x8 pa1, bf16x8 pa2, bf16x8 pa3) {
; #pragma unroll
;     for (int d0 = 0; d0 < 2; ++d0) { s16x4 lo[4], hi[4];
; #pragma unroll
;         for (int ks = 0; ks < 4; ++ks) {
; template <bool BAND>
; __device__ __forceinline__ void tile_body(f32x16* o, float& l_reg, const bf16x8* qr, const LAS unsigned char* kbs, const LAS float* wb, int vb, float ci, int hi, int keybase, int qabs) {
;     ...
; #pragma unroll
;     for (int g4 = 0; g4 < 4; ++g4) {
;         const f32x4 ba = *(const LAS f32x4*)(wb + 8 * g4 + 4 * hi) + ci, bb = *(const LAS f32x4*)(wb + 32 + 8 * g4 + 4 * hi) + ci;
; #pragma unroll
;         for (int e = 0; e < 4; ++e) { p0[4 * g4 + e] = ba[e]; p1[4 * g4 + e] = bb[e]; }
;     }
; #pragma unroll
;     for (int d0 = 0; d0 < 4; ++d0) {
;         const bf16x8 b0 = *(const LAS bf16x8*)(kbs + d0 * 2048), b1 = *(const LAS bf16x8*)(kbs + d0 * 2048 + 512);
;         p0 = __builtin_amdgcn_mfma_f32_32x32x16_bf16(b0, qr[d0], p0, 0, 0, 0); p1 = __builtin_amdgcn_mfma_f32_32x32x16_bf16(b1, qr[d0], p1, 0, 0, 0); }
;     if (BAND) {
; #pragma unroll
;         for (int r = 0; r < 16; ++r) { const int key = keybase + 8 * (r >> 2) + (r & 3); if (key > qabs) p0[r] = -INFINITY; if (key + 32 > qabs) p1[r] = -INFINITY; }
;     }
;     f32x2 s2 = {0.f, 0.f};
; #pragma unroll
;     for (int r = 0; r < 16; r += 2) {
;         p0[r] = __builtin_amdgcn_exp2f(p0[r]); p0[r + 1] = __builtin_amdgcn_exp2f(p0[r + 1]); p1[r] = __builtin_amdgcn_exp2f(p1[r]); p1[r + 1] = __builtin_amdgcn_exp2f(p1[r + 1]);
;         s2 += (f32x2){p0[r], p0[r + 1]}; s2 += (f32x2){p1[r], p1[r + 1]}; }
;     l_reg += s2.x + s2.y;
;     u32x4 pw0, pw1, pw2, pw3;
;     pw0 = (u32x4){cvtpk(p0[0], p0[1]), cvtpk(p0[2], p0[3]), cvtpk(p0[4], p0[5]), cvtpk(p0[6], p0[7])};
;     pw1 = (u32x4){cvtpk(p0[8], p0[9]), cvtpk(p0[10], p0[11]), cvtpk(p0[12], p0[13]), cvtpk(p0[14], p0[15])};
;     pw2 = (u32x4){cvtpk(p1[0], p1[1]), cvtpk(p1[2], p1[3]), cvtpk(p1[4], p1[5]), cvtpk(p1[6], p1[7])};
;     pw3 = (u32x4){cvtpk(p1[8], p1[9]), cvtpk(p1[10], p1[11]), cvtpk(p1[12], p1[13]), cvtpk(p1[14], p1[15])};
;     pv(o, vb, __builtin_bit_cast(bf16x8, pw0), __builtin_bit_cast(bf16x8, pw1), __builtin_bit_cast(bf16x8, pw2), __builtin_bit_cast(bf16x8, pw3));
.LBB0_789:
	s_andn2_b64 vcc, exec, s[64:65]
	s_cbranch_vccnz .Lmy_attjoin_A
	s_nop 4
	ds_read_b128 v[34:37], v153 offset:32768
	ds_read_b128 v[38:41], v153 offset:32800
	ds_read_b128 v[42:45], v153 offset:32832
	ds_read_b128 v[46:49], v153 offset:32864
	s_nop 0
	ds_read_b128 v[50:53], v153 offset:32896
	ds_read_b128 v[54:57], v153 offset:32928
	ds_read_b128 v[58:61], v153 offset:32960
	ds_read_b128 v[62:65], v153 offset:32992
	ds_read_b128 v[154:157], v152
	ds_read_b128 v[158:161], v152 offset:512
	s_waitcnt lgkmcnt(6)
	ds_read_b128 v[210:213], v152 offset:2048
	ds_read_b128 v[214:217], v152 offset:2560
	ds_read_b128 v[218:221], v152 offset:4096
	ds_read_b128 v[222:225], v152 offset:4608
	ds_read_b128 v[226:229], v152 offset:6144
	ds_read_b128 v[230:233], v152 offset:6656
	v_pk_add_f32 v[48:49], v[126:127], v[48:49]
	v_pk_add_f32 v[44:45], v[122:123], v[44:45]
	v_pk_add_f32 v[40:41], v[118:119], v[40:41]
	v_pk_add_f32 v[36:37], v[114:115], v[36:37]
	v_pk_add_f32 v[46:47], v[124:125], v[46:47]
	v_pk_add_f32 v[42:43], v[120:121], v[42:43]
	v_pk_add_f32 v[38:39], v[116:117], v[38:39]
	v_pk_add_f32 v[34:35], v[112:113], v[34:35]
	s_waitcnt lgkmcnt(8)
	v_pk_add_f32 v[64:65], v[126:127], v[64:65]
	v_pk_add_f32 v[60:61], v[122:123], v[60:61]
	s_waitcnt lgkmcnt(7)
	v_mfma_f32_32x32x16_bf16 v[34:49], v[154:157], v[94:97], v[34:49]
	v_add_f32_e64 v56, v118, v56
	v_add_f32_e64 v57, v119, v57
	v_add_f32_e64 v52, v114, v52
	v_add_f32_e64 v53, v115, v53
	v_add_f32_e64 v62, v124, v62
	v_add_f32_e64 v63, v125, v63
	v_pk_add_f32 v[58:59], v[120:121], v[58:59]
	v_pk_add_f32 v[54:55], v[116:117], v[54:55]
	v_pk_add_f32 v[50:51], v[112:113], v[50:51]
	s_waitcnt lgkmcnt(6)
	s_nop 0
	v_mfma_f32_32x32x16_bf16 v[50:65], v[158:161], v[94:97], v[50:65]
	s_waitcnt lgkmcnt(5)
	v_mfma_f32_32x32x16_bf16 v[34:49], v[210:213], v[98:101], v[34:49]
	s_waitcnt lgkmcnt(4)
	v_mfma_f32_32x32x16_bf16 v[50:65], v[214:217], v[98:101], v[50:65]
	s_waitcnt lgkmcnt(3)
	v_mfma_f32_32x32x16_bf16 v[34:49], v[218:221], v[102:105], v[34:49]
	s_waitcnt lgkmcnt(2)
	v_mfma_f32_32x32x16_bf16 v[50:65], v[222:225], v[102:105], v[50:65]
	s_waitcnt lgkmcnt(1)
	v_mfma_f32_32x32x16_bf16 v[34:49], v[226:229], v[90:93], v[34:49]
	s_waitcnt lgkmcnt(0)
	v_mfma_f32_32x32x16_bf16 v[50:65], v[230:233], v[90:93], v[50:65]
	s_nop 9
	v_exp_f32_e32 v34, v34
	v_exp_f32_e32 v35, v35
	v_exp_f32_e32 v36, v36
	v_exp_f32_e32 v37, v37
	v_exp_f32_e32 v38, v38
	v_pk_add_f32 v[152:153], v[34:35], 0 op_sel_hi:[1,0]
	v_exp_f32_e32 v39, v39
	v_exp_f32_e32 v50, v50
	v_exp_f32_e32 v51, v51
	v_exp_f32_e32 v52, v52
	v_exp_f32_e32 v53, v53
	v_exp_f32_e32 v54, v54
	v_pk_add_f32 v[152:153], v[50:51], v[152:153]
	v_exp_f32_e32 v55, v55
	v_pk_add_f32 v[152:153], v[36:37], v[152:153]
	v_exp_f32_e32 v40, v40
	v_exp_f32_e32 v41, v41
	v_pk_add_f32 v[152:153], v[52:53], v[152:153]
	v_exp_f32_e32 v56, v56
	v_exp_f32_e32 v57, v57
	v_pk_add_f32 v[152:153], v[38:39], v[152:153]
	v_exp_f32_e32 v42, v42
	v_exp_f32_e32 v43, v43
	v_pk_add_f32 v[152:153], v[54:55], v[152:153]
	v_exp_f32_e32 v58, v58
	v_exp_f32_e32 v59, v59
	v_pk_add_f32 v[152:153], v[40:41], v[152:153]
	v_exp_f32_e32 v44, v44
	v_exp_f32_e32 v45, v45
	v_pk_add_f32 v[152:153], v[56:57], v[152:153]
	v_exp_f32_e32 v60, v60
	v_exp_f32_e32 v61, v61
	v_pk_add_f32 v[152:153], v[42:43], v[152:153]
	v_exp_f32_e32 v46, v46
	v_exp_f32_e32 v47, v47
	v_cvt_pk_bf16_f32 v34, v34, v35
	v_cvt_pk_bf16_f32 v35, v36, v37
	v_cvt_pk_bf16_f32 v36, v38, v39
	v_cvt_pk_bf16_f32 v38, v42, v43
	v_cvt_pk_bf16_f32 v42, v50, v51
	ds_read_b64_tr_b16 v[50:51],v151 offset:0
	v_pk_add_f32 v[152:153], v[58:59], v[152:153]
	v_exp_f32_e32 v62, v62
	v_exp_f32_e32 v63, v63
	v_cvt_pk_bf16_f32 v43, v52, v53
	ds_read_b64_tr_b16 v[52:53],v151 offset:512
	v_pk_add_f32 v[152:153], v[44:45], v[152:153]
	v_exp_f32_e32 v48, v48
	v_exp_f32_e32 v49, v49
	v_cvt_pk_bf16_f32 v39, v44, v45
	v_cvt_pk_bf16_f32 v44, v54, v55
	ds_read_b64_tr_b16 v[54:55],v151 offset:1024
	v_pk_add_f32 v[152:153], v[60:61], v[152:153]
	v_exp_f32_e32 v64, v64
	v_exp_f32_e32 v65, v65
	v_cvt_pk_bf16_f32 v45, v56, v57
	ds_read_b64_tr_b16 v[56:57],v151 offset:1536
	v_pk_add_f32 v[152:153], v[46:47], v[152:153]
	v_cvt_pk_bf16_f32 v37, v40, v41
	v_cvt_pk_bf16_f32 v40, v46, v47
	v_cvt_pk_bf16_f32 v46, v58, v59
	ds_read_b64_tr_b16 v[58:59],v151 offset:2048
	v_pk_add_f32 v[152:153], v[62:63], v[152:153]
	v_cvt_pk_bf16_f32 v47, v60, v61
	ds_read_b64_tr_b16 v[60:61],v151 offset:2560
	v_pk_add_f32 v[152:153], v[48:49], v[152:153]
	v_cvt_pk_bf16_f32 v41, v48, v49
	v_cvt_pk_bf16_f32 v48, v62, v63
	ds_read_b64_tr_b16 v[62:63],v151 offset:3072
	v_pk_add_f32 v[152:153], v[64:65], v[152:153]
	v_cvt_pk_bf16_f32 v49, v64, v65
	ds_read_b64_tr_b16 v[64:65],v151 offset:3584
	s_waitcnt lgkmcnt(0)
	v_add_f32_e32 v152, v152, v153
	v_add_f32_e32 v154, v148, v152
	v_mfma_f32_32x32x16_bf16 v[2:17], v[34:37], v[50:53], v[2:17]
	ds_read_b64_tr_b16 v[50:51],v151 offset:4096
	ds_read_b64_tr_b16 v[52:53],v151 offset:4608
	v_mfma_f32_32x32x16_bf16 v[2:17], v[38:41], v[54:57], v[2:17]
	ds_read_b64_tr_b16 v[54:55],v151 offset:5120
	ds_read_b64_tr_b16 v[56:57],v151 offset:5632
	v_mfma_f32_32x32x16_bf16 v[2:17], v[42:45], v[58:61], v[2:17]
	ds_read_b64_tr_b16 v[58:59],v151 offset:6144
	ds_read_b64_tr_b16 v[60:61],v151 offset:6656
	ds_read_b64_tr_b16 v[156:157],v151 offset:7168
	ds_read_b64_tr_b16 v[158:159],v151 offset:7680
	s_waitcnt lgkmcnt(0)
	v_mfma_f32_32x32x16_bf16 v[2:17], v[46:49], v[62:65], v[2:17]
	v_mfma_f32_32x32x16_bf16 v[18:33], v[34:37], v[50:53], v[18:33]
	v_mfma_f32_32x32x16_bf16 v[18:33], v[38:41], v[54:57], v[18:33]
	v_mfma_f32_32x32x16_bf16 v[18:33], v[42:45], v[58:61], v[18:33]
	v_mfma_f32_32x32x16_bf16 v[18:33], v[46:49], v[156:159], v[18:33]

; #define LAS __attribute__((address_space(3)))
; template <bool BAND>
; __device__ __forceinline__ void tile_body(f32x16* o, float& l_reg, const bf16x8* qr, const LAS unsigned char* kbs, const LAS float* wb, int vb, float ci, int hi, int keybase, int qabs) {
;     ...
; #pragma unroll
;     for (int g4 = 0; g4 < 4; ++g4) {
;         const f32x4 ba = *(const LAS f32x4*)(wb + 8 * g4 + 4 * hi) + ci, bb = *(const LAS f32x4*)(wb + 32 + 8 * g4 + 4 * hi) + ci;
; #pragma unroll
;         for (int e = 0; e < 4; ++e) { p0[4 * g4 + e] = ba[e]; p1[4 * g4 + e] = bb[e]; }
;     }
; #pragma unroll
;     for (int d0 = 0; d0 < 4; ++d0) {
;         const bf16x8 b0 = *(const LAS bf16x8*)(kbs + d0 * 2048), b1 = *(const LAS bf16x8*)(kbs + d0 * 2048 + 512);
;         p0 = __builtin_amdgcn_mfma_f32_32x32x16_bf16(b0, qr[d0], p0, 0, 0, 0); p1 = __builtin_amdgcn_mfma_f32_32x32x16_bf16(b1, qr[d0], p1, 0, 0, 0); }
;     if (BAND) {
; #pragma unroll
;         for (int r = 0; r < 16; ++r) { const int key = keybase + 8 * (r >> 2) + (r & 3); if (key > qabs) p0[r] = -INFINITY; if (key + 32 > qabs) p1[r] = -INFINITY; }
;     }
;     f32x2 s2 = {0.f, 0.f};
; #pragma unroll
;     for (int r = 0; r < 16; r += 2) {
;         p0[r] = __builtin_amdgcn_exp2f(p0[r]); p0[r + 1] = __builtin_amdgcn_exp2f(p0[r + 1]); p1[r] = __builtin_amdgcn_exp2f(p1[r]); p1[r + 1] = __builtin_amdgcn_exp2f(p1[r + 1]);
;         s2 += (f32x2){p0[r], p0[r + 1]}; s2 += (f32x2){p1[r], p1[r + 1]}; }
;     l_reg += s2.x + s2.y;
.LBB0_799:
	s_andn2_saveexec_b64 s[66:67], s[66:67]
	v_mov_b32_e32 v151, s79
	v_add_f32_e32 v151, s28, v151
	v_add_f32_e32 v153, s77, v151
	s_or_b64 exec, exec, s[66:67]
	v_add_f32_e32 v151, s76, v150
	v_add_f32_e32 v150, v152, v153
	v_add_f32_e32 v152, v151, v150
	s_lshl_b32 s28, s70, 8
	v_sub_f32_e32 v141, v152, v141
	s_add_i32 s76, s53, s28
	v_mul_f32_e32 v141, 0x3fb8aa3b, v141
	v_lshl_add_u32 v152, v137, 2, s76
	s_lshl_b32 s77, s70, 14
	ds_write_b32 v152, v141 offset:32768
	v_add_u32_e32 v141, s77, v143
	s_max_i32 s28, s48, 5
	ds_write_b128 v141, v[70:73]
	ds_write_b128 v141, v[82:85] offset:8192
	s_add_i32 s28, s28, -5
	s_waitcnt lgkmcnt(0)
	s_lshl_b64 s[66:67], s[28:29], 11
	v_lshl_add_u64 v[70:71], v[110:111], 0, s[66:67]
	global_load_dword v141, v[70:71], off
	s_lshl_b64 s[66:67], s[28:29], 16
	v_lshl_add_u64 v[82:83], v[106:107], 0, s[66:67]
	global_load_dwordx4 v[70:73], v[82:83], off
	v_lshl_add_u64 v[152:153], v[108:109], 0, s[66:67]
	global_load_dwordx4 v[82:85], v[152:153], off
	v_readfirstlane_b32 s79, v150
	s_and_b64 vcc, exec, s[12:13]
	s_cbranch_vccnz .LBB0_808
	s_and_b64 vcc, exec, s[98:99]
	s_cbranch_vccnz .LBB0_808
	s_add_i32 s28, s75, 0xffffff80
	s_cmp_gt_i32 s28, s73
	s_cbranch_scc1 .LBB0_808
	s_cmp_le_i32 s48, s72
	v_add_u32_e32 v150, s78, v144
	s_mov_b64 s[66:67], -1
	v_add_u32_e32 v152, s78, v145
	v_lshl_add_u32 v153, v142, 2, s71
	s_cbranch_scc0 .LBB0_805
	ds_read_b128 v[34:37], v153 offset:32768
	ds_read_b128 v[38:41], v153 offset:32800
	ds_read_b128 v[42:45], v153 offset:32832
	ds_read_b128 v[46:49], v153 offset:32864
	ds_read_b128 v[50:53], v153 offset:32896
	ds_read_b128 v[54:57], v153 offset:32928
	ds_read_b128 v[58:61], v153 offset:32960
	ds_read_b128 v[62:65], v153 offset:32992
	ds_read_b128 v[154:157], v152
	ds_read_b128 v[158:161], v152 offset:512
	s_waitcnt lgkmcnt(6)
	ds_read_b128 v[210:213], v152 offset:2048
	ds_read_b128 v[214:217], v152 offset:2560
	ds_read_b128 v[218:221], v152 offset:4096
	ds_read_b128 v[222:225], v152 offset:4608
	ds_read_b128 v[226:229], v152 offset:6144
	ds_read_b128 v[230:233], v152 offset:6656
	v_pk_add_f32 v[48:49], v[126:127], v[48:49]
	v_pk_add_f32 v[44:45], v[122:123], v[44:45]
	v_pk_add_f32 v[40:41], v[118:119], v[40:41]
	v_pk_add_f32 v[36:37], v[114:115], v[36:37]
	v_pk_add_f32 v[46:47], v[124:125], v[46:47]
	v_pk_add_f32 v[42:43], v[120:121], v[42:43]
	v_pk_add_f32 v[38:39], v[116:117], v[38:39]
	v_pk_add_f32 v[34:35], v[112:113], v[34:35]
	s_waitcnt lgkmcnt(8)
	v_pk_add_f32 v[64:65], v[126:127], v[64:65]
	v_pk_add_f32 v[60:61], v[122:123], v[60:61]
	s_waitcnt lgkmcnt(7)
	v_mfma_f32_32x32x16_bf16 v[34:49], v[154:157], v[94:97], v[34:49]
	v_add_f32_e64 v56, v118, v56
	v_add_f32_e64 v57, v119, v57
	v_add_f32_e64 v52, v114, v52
	v_add_f32_e64 v53, v115, v53
	v_add_f32_e64 v62, v124, v62
	v_add_f32_e64 v63, v125, v63
	v_pk_add_f32 v[58:59], v[120:121], v[58:59]
	v_pk_add_f32 v[54:55], v[116:117], v[54:55]
	v_pk_add_f32 v[50:51], v[112:113], v[50:51]
	s_waitcnt lgkmcnt(6)
	s_nop 0
	v_mfma_f32_32x32x16_bf16 v[50:65], v[158:161], v[94:97], v[50:65]
	s_waitcnt lgkmcnt(5)
	v_mfma_f32_32x32x16_bf16 v[34:49], v[210:213], v[98:101], v[34:49]
	s_waitcnt lgkmcnt(4)
	v_mfma_f32_32x32x16_bf16 v[50:65], v[214:217], v[98:101], v[50:65]
	s_waitcnt lgkmcnt(3)
	v_mfma_f32_32x32x16_bf16 v[34:49], v[218:221], v[102:105], v[34:49]
	s_waitcnt lgkmcnt(2)
	v_mfma_f32_32x32x16_bf16 v[50:65], v[222:225], v[102:105], v[50:65]
	s_waitcnt lgkmcnt(1)
	v_mfma_f32_32x32x16_bf16 v[34:49], v[226:229], v[90:93], v[34:49]
	s_waitcnt lgkmcnt(0)
	v_mfma_f32_32x32x16_bf16 v[50:65], v[230:233], v[90:93], v[50:65]
	s_nop 9
	v_exp_f32_e32 v34, v34
	v_exp_f32_e32 v35, v35
	v_exp_f32_e32 v36, v36
	v_exp_f32_e32 v37, v37
	v_exp_f32_e32 v38, v38
	v_pk_add_f32 v[154:155], v[34:35], 0 op_sel_hi:[1,0]
	v_exp_f32_e32 v39, v39
	v_exp_f32_e32 v50, v50
	v_exp_f32_e32 v51, v51
	v_exp_f32_e32 v52, v52
	v_exp_f32_e32 v53, v53
	v_exp_f32_e32 v54, v54
	v_pk_add_f32 v[154:155], v[50:51], v[154:155]
	v_exp_f32_e32 v55, v55
	v_pk_add_f32 v[154:155], v[36:37], v[154:155]
	v_exp_f32_e32 v40, v40
	v_exp_f32_e32 v41, v41
	v_pk_add_f32 v[154:155], v[52:53], v[154:155]
	v_exp_f32_e32 v56, v56
	v_exp_f32_e32 v57, v57
	v_pk_add_f32 v[154:155], v[38:39], v[154:155]
	v_exp_f32_e32 v42, v42
	v_exp_f32_e32 v43, v43
	v_pk_add_f32 v[154:155], v[54:55], v[154:155]
	v_exp_f32_e32 v58, v58
	v_exp_f32_e32 v59, v59
	v_pk_add_f32 v[154:155], v[40:41], v[154:155]
	v_exp_f32_e32 v44, v44
	v_exp_f32_e32 v45, v45
	v_pk_add_f32 v[154:155], v[56:57], v[154:155]
	v_exp_f32_e32 v60, v60
	v_exp_f32_e32 v61, v61
	v_pk_add_f32 v[154:155], v[42:43], v[154:155]
	v_exp_f32_e32 v46, v46
	v_exp_f32_e32 v47, v47
	v_cvt_pk_bf16_f32 v164, v50, v51
	ds_read_b64_tr_b16 v[50:51],v150 offset:0
	v_pk_add_f32 v[154:155], v[58:59], v[154:155]
	v_exp_f32_e32 v62, v62
	v_exp_f32_e32 v63, v63
	v_cvt_pk_bf16_f32 v165, v52, v53
	ds_read_b64_tr_b16 v[52:53],v150 offset:512
	v_pk_add_f32 v[154:155], v[44:45], v[154:155]
	v_exp_f32_e32 v48, v48
	v_exp_f32_e32 v49, v49
	v_cvt_pk_bf16_f32 v166, v54, v55
	ds_read_b64_tr_b16 v[54:55],v150 offset:1024
	v_pk_add_f32 v[154:155], v[60:61], v[154:155]
	v_exp_f32_e32 v64, v64
	v_exp_f32_e32 v65, v65
	v_cvt_pk_bf16_f32 v167, v56, v57
	ds_read_b64_tr_b16 v[56:57],v150 offset:1536
	v_pk_add_f32 v[154:155], v[46:47], v[154:155]
	v_cvt_pk_bf16_f32 v168, v58, v59
	ds_read_b64_tr_b16 v[58:59],v150 offset:2048
	v_pk_add_f32 v[154:155], v[62:63], v[154:155]
	v_cvt_pk_bf16_f32 v169, v60, v61
	ds_read_b64_tr_b16 v[60:61],v150 offset:2560
	v_pk_add_f32 v[154:155], v[48:49], v[154:155]
	v_cvt_pk_bf16_f32 v170, v62, v63
	ds_read_b64_tr_b16 v[62:63],v150 offset:3072
	v_pk_add_f32 v[154:155], v[64:65], v[154:155]
	v_cvt_pk_bf16_f32 v171, v64, v65
	ds_read_b64_tr_b16 v[64:65],v150 offset:3584
	s_waitcnt lgkmcnt(0)
; #define LAS __attribute__((address_space(3)))
; __device__ __forceinline__ unsigned cvtpk(float lo, float hi) { typedef __bf16 bf16x2_t __attribute__((ext_vector_type(2))); f32x2 v = {lo, hi}; bf16x2_t b = __builtin_convertvector(v, bf16x2_t); return __builtin_bit_cast(unsigned, b); }
; template <bool BAND>
; __device__ __forceinline__ void tile_body(f32x16* o, float& l_reg, const bf16x8* qr, const LAS unsigned char* kbs, const LAS float* wb, int vb, float ci, int hi, int keybase, int qabs) {
;     ...
; #pragma unroll
;     for (int g4 = 0; g4 < 4; ++g4) {
;         const f32x4 ba = *(const LAS f32x4*)(wb + 8 * g4 + 4 * hi) + ci, bb = *(const LAS f32x4*)(wb + 32 + 8 * g4 + 4 * hi) + ci;
; #pragma unroll
;         for (int e = 0; e < 4; ++e) { p0[4 * g4 + e] = ba[e]; p1[4 * g4 + e] = bb[e]; }
;     }
; #pragma unroll
;     for (int d0 = 0; d0 < 4; ++d0) {
;         const bf16x8 b0 = *(const LAS bf16x8*)(kbs + d0 * 2048), b1 = *(const LAS bf16x8*)(kbs + d0 * 2048 + 512);
;         p0 = __builtin_amdgcn_mfma_f32_32x32x16_bf16(b0, qr[d0], p0, 0, 0, 0); p1 = __builtin_amdgcn_mfma_f32_32x32x16_bf16(b1, qr[d0], p1, 0, 0, 0); }
;     ...
;     u32x4 pw0, pw1, pw2, pw3;
;     pw0 = (u32x4){cvtpk(p0[0], p0[1]), cvtpk(p0[2], p0[3]), cvtpk(p0[4], p0[5]), cvtpk(p0[6], p0[7])};
;     pw1 = (u32x4){cvtpk(p0[8], p0[9]), cvtpk(p0[10], p0[11]), cvtpk(p0[12], p0[13]), cvtpk(p0[14], p0[15])};
;     pw2 = (u32x4){cvtpk(p1[0], p1[1]), cvtpk(p1[2], p1[3]), cvtpk(p1[4], p1[5]), cvtpk(p1[6], p1[7])};
;     pw3 = (u32x4){cvtpk(p1[8], p1[9]), cvtpk(p1[10], p1[11]), cvtpk(p1[12], p1[13]), cvtpk(p1[14], p1[15])};
;     pv(o, vb, __builtin_bit_cast(bf16x8, pw0), __builtin_bit_cast(bf16x8, pw1), __builtin_bit_cast(bf16x8, pw2), __builtin_bit_cast(bf16x8, pw3));
	v_add_f32_e32 v154, v154, v155
	v_add_f32_e32 v154, v148, v154
	v_cvt_pk_bf16_f32 v156, v34, v35
	v_cvt_pk_bf16_f32 v157, v36, v37
	v_cvt_pk_bf16_f32 v158, v38, v39
	v_cvt_pk_bf16_f32 v159, v40, v41
	v_cvt_pk_bf16_f32 v160, v42, v43
	v_cvt_pk_bf16_f32 v161, v44, v45
	v_cvt_pk_bf16_f32 v162, v46, v47
	v_cvt_pk_bf16_f32 v163, v48, v49
	v_mfma_f32_32x32x16_bf16 v[2:17], v[156:159], v[50:53], v[2:17]
	ds_read_b64_tr_b16 v[172:173],v150 offset:4096
	ds_read_b64_tr_b16 v[174:175],v150 offset:4608
	ds_read_b64_tr_b16 v[176:177],v150 offset:5120
	ds_read_b64_tr_b16 v[178:179],v150 offset:5632
	ds_read_b64_tr_b16 v[180:181],v150 offset:6144
	ds_read_b64_tr_b16 v[182:183],v150 offset:6656
	ds_read_b64_tr_b16 v[184:185],v150 offset:7168
	s_nop 0
	v_mfma_f32_32x32x16_bf16 v[2:17], v[160:163], v[54:57], v[2:17]
	ds_read_b64_tr_b16 v[186:187],v150 offset:7680
	s_waitcnt lgkmcnt(0)
	v_mfma_f32_32x32x16_bf16 v[2:17], v[164:167], v[58:61], v[2:17]
	v_mfma_f32_32x32x16_bf16 v[2:17], v[168:171], v[62:65], v[2:17]
	v_mfma_f32_32x32x16_bf16 v[18:33], v[156:159], v[172:175], v[18:33]
	s_mov_b64 s[66:67], 0
	v_mfma_f32_32x32x16_bf16 v[18:33], v[160:163], v[176:179], v[18:33]
	v_mfma_f32_32x32x16_bf16 v[18:33], v[164:167], v[180:183], v[18:33]
	v_mfma_f32_32x32x16_bf16 v[18:33], v[168:171], v[184:187], v[18:33]
.LBB0_805:
	s_andn2_b64 vcc, exec, s[66:67]
	s_cbranch_vccnz .Lmy_attjoin_B
	s_nop 4
	ds_read_b128 v[34:37], v153 offset:32768
	ds_read_b128 v[38:41], v153 offset:32800
	ds_read_b128 v[42:45], v153 offset:32832
	ds_read_b128 v[46:49], v153 offset:32864
	s_nop 0
	ds_read_b128 v[50:53], v153 offset:32896
	ds_read_b128 v[54:57], v153 offset:32928
	ds_read_b128 v[58:61], v153 offset:32960
	ds_read_b128 v[62:65], v153 offset:32992
	ds_read_b128 v[154:157], v152
	ds_read_b128 v[158:161], v152 offset:512
	s_waitcnt lgkmcnt(4)
	ds_read_b128 v[210:213], v152 offset:2048
	ds_read_b128 v[214:217], v152 offset:2560
	ds_read_b128 v[218:221], v152 offset:4096
	ds_read_b128 v[222:225], v152 offset:4608
	ds_read_b128 v[226:229], v152 offset:6656
	ds_read_b128 v[230:233], v152 offset:6144
	v_pk_add_f32 v[56:57], v[118:119], v[56:57]
	s_waitcnt lgkmcnt(9)
	v_pk_add_f32 v[60:61], v[122:123], v[60:61]
	s_waitcnt lgkmcnt(8)
	v_pk_add_f32 v[64:65], v[126:127], v[64:65]
	v_pk_add_f32 v[52:53], v[114:115], v[52:53]
	v_pk_add_f32 v[62:63], v[124:125], v[62:63]
	v_pk_add_f32 v[58:59], v[120:121], v[58:59]
	v_pk_add_f32 v[54:55], v[116:117], v[54:55]
	v_pk_add_f32 v[50:51], v[112:113], v[50:51]
	v_pk_add_f32 v[48:49], v[126:127], v[48:49]
	v_pk_add_f32 v[44:45], v[122:123], v[44:45]
	v_pk_add_f32 v[40:41], v[118:119], v[40:41]
	v_pk_add_f32 v[36:37], v[114:115], v[36:37]
	v_pk_add_f32 v[46:47], v[124:125], v[46:47]
	v_pk_add_f32 v[42:43], v[120:121], v[42:43]
	v_pk_add_f32 v[38:39], v[116:117], v[38:39]
	v_pk_add_f32 v[34:35], v[112:113], v[34:35]
	s_waitcnt lgkmcnt(6)
	v_mfma_f32_32x32x16_bf16 v[50:65], v[158:161], v[94:97], v[50:65]
	v_mfma_f32_32x32x16_bf16 v[34:49], v[154:157], v[94:97], v[34:49]
	s_waitcnt lgkmcnt(4)
	v_mfma_f32_32x32x16_bf16 v[50:65], v[214:217], v[98:101], v[50:65]
	v_mfma_f32_32x32x16_bf16 v[34:49], v[210:213], v[98:101], v[34:49]
	s_waitcnt lgkmcnt(2)
	v_mfma_f32_32x32x16_bf16 v[50:65], v[222:225], v[102:105], v[50:65]
	v_mfma_f32_32x32x16_bf16 v[34:49], v[218:221], v[102:105], v[34:49]
	v_add_u32_e32 v152, s75, v142
	v_add_u32_e32 v153, 0xffffff80, v152
	s_waitcnt lgkmcnt(1)
	v_mfma_f32_32x32x16_bf16 v[50:65], v[226:229], v[90:93], v[50:65]
	v_add_u32_e32 v154, 0xffffffa0, v152
	v_cmp_le_i32_e32 vcc, v154, v147
	s_waitcnt lgkmcnt(0)
; __device__ __forceinline__ void pv(f32x16* o, int vb, bf16x8 pa0, bf16x8 pa1, bf16x8 pa2, bf16x8 pa3) {
; #pragma unroll
;     for (int d0 = 0; d0 < 2; ++d0) { s16x4 lo[4], hi[4];
; #pragma unroll
;         for (int ks = 0; ks < 4; ++ks) {
;             asm volatile("ds_read_b64_tr_b16 %0,%1 offset:%c2" : "=&v"(lo[ks]) : "v"(vb), "i"(d0 * 4096 + ks * 1024) : "memory");
;             asm volatile("ds_read_b64_tr_b16 %0,%1 offset:%c2" : "=&v"(hi[ks]) : "v"(vb), "i"(d0 * 4096 + ks * 1024 + 512) : "memory"); }
;         asm volatile("s_waitcnt lgkmcnt(0)" ::: "memory"); __builtin_amdgcn_sched_barrier(0);
;     ...
;         o[d0] = __builtin_amdgcn_mfma_f32_32x32x16_bf16(pa0, PK(0), o[d0], 0, 0, 0);
;         o[d0] = __builtin_amdgcn_mfma_f32_32x32x16_bf16(pa1, PK(1), o[d0], 0, 0, 0);
;         o[d0] = __builtin_amdgcn_mfma_f32_32x32x16_bf16(pa2, PK(2), o[d0], 0, 0, 0);
;         o[d0] = __builtin_amdgcn_mfma_f32_32x32x16_bf16(pa3, PK(3), o[d0], 0, 0, 0);
; template <bool BAND>
; __device__ __forceinline__ void tile_body(f32x16* o, float& l_reg, const bf16x8* qr, const LAS unsigned char* kbs, const LAS float* wb, int vb, float ci, int hi, int keybase, int qabs) {
;     ...
;     if (BAND) {
; #pragma unroll
;         for (int r = 0; r < 16; ++r) { const int key = keybase + 8 * (r >> 2) + (r & 3); if (key > qabs) p0[r] = -INFINITY; if (key + 32 > qabs) p1[r] = -INFINITY; }
;     }
;     f32x2 s2 = {0.f, 0.f};
; #pragma unroll
;     for (int r = 0; r < 16; r += 2) {
;         p0[r] = __builtin_amdgcn_exp2f(p0[r]); p0[r + 1] = __builtin_amdgcn_exp2f(p0[r + 1]); p1[r] = __builtin_amdgcn_exp2f(p1[r]); p1[r + 1] = __builtin_amdgcn_exp2f(p1[r + 1]);
;         s2 += (f32x2){p0[r], p0[r + 1]}; s2 += (f32x2){p1[r], p1[r + 1]}; }
;     l_reg += s2.x + s2.y;
;     u32x4 pw0, pw1, pw2, pw3;
;     pw0 = (u32x4){cvtpk(p0[0], p0[1]), cvtpk(p0[2], p0[3]), cvtpk(p0[4], p0[5]), cvtpk(p0[6], p0[7])};
;     pw1 = (u32x4){cvtpk(p0[8], p0[9]), cvtpk(p0[10], p0[11]), cvtpk(p0[12], p0[13]), cvtpk(p0[14], p0[15])};
;     pw2 = (u32x4){cvtpk(p1[0], p1[1]), cvtpk(p1[2], p1[3]), cvtpk(p1[4], p1[5]), cvtpk(p1[6], p1[7])};
;     pw3 = (u32x4){cvtpk(p1[8], p1[9]), cvtpk(p1[10], p1[11]), cvtpk(p1[12], p1[13]), cvtpk(p1[14], p1[15])};
;     pv(o, vb, __builtin_bit_cast(bf16x8, pw0), __builtin_bit_cast(bf16x8, pw1), __builtin_bit_cast(bf16x8, pw2), __builtin_bit_cast(bf16x8, pw3));
	v_mfma_f32_32x32x16_bf16 v[34:49], v[230:233], v[90:93], v[34:49]
	s_nop 7
	v_cndmask_b32_e32 v50, v134, v50, vcc
	v_cmp_lt_i32_e32 vcc, v153, v147
	s_nop 1
	v_cndmask_b32_e32 v35, v134, v35, vcc
	v_cmp_le_i32_e32 vcc, v153, v147
	v_add_u32_e32 v153, 0xffffffa1, v152
	v_exp_f32_e32 v35, v35
	v_cndmask_b32_e32 v34, v134, v34, vcc
	v_cmp_le_i32_e32 vcc, v153, v147
	v_add_u32_e32 v153, 0xffffff82, v152
	v_exp_f32_e32 v34, v34
	v_cndmask_b32_e32 v51, v134, v51, vcc
	v_cmp_le_i32_e32 vcc, v153, v147
	v_add_u32_e32 v153, 0xffffffa2, v152
	s_nop 0
	v_cndmask_b32_e32 v36, v134, v36, vcc
	v_cmp_le_i32_e32 vcc, v153, v147
	v_add_u32_e32 v153, 0xffffff83, v152
	v_exp_f32_e32 v36, v36
	v_cndmask_b32_e32 v52, v134, v52, vcc
	v_cmp_le_i32_e32 vcc, v153, v147
	v_add_u32_e32 v153, 0xffffffa3, v152
	s_nop 0
	v_cndmask_b32_e32 v37, v134, v37, vcc
	v_cmp_le_i32_e32 vcc, v153, v147
	v_add_u32_e32 v153, 0xffffff88, v152
	v_exp_f32_e32 v37, v37
	v_cndmask_b32_e32 v53, v134, v53, vcc
	v_cmp_le_i32_e32 vcc, v153, v147
	s_nop 1
	v_cndmask_b32_e32 v153, v134, v38, vcc
	v_add_u32_e32 v38, 0xffffffa8, v152
	v_cmp_le_i32_e32 vcc, v38, v147
	v_add_u32_e32 v38, 0xffffff89, v152
	s_nop 0
	v_cndmask_b32_e32 v54, v134, v54, vcc
	v_cmp_le_i32_e32 vcc, v38, v147
	v_add_u32_e32 v38, 0xffffffa9, v152
	s_nop 0
	v_cndmask_b32_e32 v154, v134, v39, vcc
	v_cmp_le_i32_e32 vcc, v38, v147
	v_add_u32_e32 v38, 0xffffff8a, v152
	s_nop 0
	v_cndmask_b32_e32 v55, v134, v55, vcc
	v_cmp_le_i32_e32 vcc, v38, v147
	v_add_u32_e32 v38, 0xffffffaa, v152
	s_nop 0
	v_cndmask_b32_e32 v155, v134, v40, vcc
	v_cmp_le_i32_e32 vcc, v38, v147
	v_add_u32_e32 v38, 0xffffff8b, v152
	v_exp_f32_e32 v40, v153
	v_cndmask_b32_e32 v56, v134, v56, vcc
	v_cmp_le_i32_e32 vcc, v38, v147
	v_add_u32_e32 v38, 0xffffffab, v152
	s_nop 0
	v_cndmask_b32_e32 v156, v134, v41, vcc
	v_cmp_le_i32_e32 vcc, v38, v147
	v_add_u32_e32 v38, 0xffffff90, v152
	v_exp_f32_e32 v41, v154
	v_cndmask_b32_e32 v57, v134, v57, vcc
	v_cmp_le_i32_e32 vcc, v38, v147
	v_add_u32_e32 v38, 0xffffffb0, v152
	s_nop 0
	v_cndmask_b32_e32 v157, v134, v42, vcc
	v_cmp_le_i32_e32 vcc, v38, v147
	v_add_u32_e32 v38, 0xffffff91, v152
	v_exp_f32_e32 v42, v50
	v_cndmask_b32_e32 v58, v134, v58, vcc
	v_cmp_le_i32_e32 vcc, v38, v147
	v_add_u32_e32 v38, 0xffffffb1, v152
	v_exp_f32_e32 v50, v56
	v_cndmask_b32_e32 v158, v134, v43, vcc
	v_cmp_le_i32_e32 vcc, v38, v147
	v_add_u32_e32 v38, 0xffffff92, v152
	v_exp_f32_e32 v43, v51
	v_cndmask_b32_e32 v59, v134, v59, vcc
	v_cmp_le_i32_e32 vcc, v38, v147
	v_add_u32_e32 v38, 0xffffffb2, v152
	v_exp_f32_e32 v51, v57
	v_cndmask_b32_e32 v159, v134, v44, vcc
	v_cmp_le_i32_e32 vcc, v38, v147
	v_add_u32_e32 v38, 0xffffff93, v152
	v_exp_f32_e32 v44, v52
	v_cndmask_b32_e32 v60, v134, v60, vcc
	v_cmp_le_i32_e32 vcc, v38, v147
	v_add_u32_e32 v38, 0xffffffb3, v152
	v_exp_f32_e32 v52, v157
	v_cndmask_b32_e32 v160, v134, v45, vcc
	v_cmp_le_i32_e32 vcc, v38, v147
	v_add_u32_e32 v38, 0xffffff98, v152
	v_exp_f32_e32 v45, v53
	v_cndmask_b32_e32 v61, v134, v61, vcc
	v_cmp_le_i32_e32 vcc, v38, v147
	v_add_u32_e32 v38, 0xffffffb8, v152
	v_exp_f32_e32 v53, v158
	v_cndmask_b32_e32 v161, v134, v46, vcc
	v_cmp_le_i32_e32 vcc, v38, v147
	v_add_u32_e32 v38, 0xffffff99, v152
	v_exp_f32_e32 v46, v54
	v_cndmask_b32_e32 v62, v134, v62, vcc
	v_cmp_le_i32_e32 vcc, v38, v147
	v_add_u32_e32 v38, 0xffffffb9, v152
	v_exp_f32_e32 v54, v58
	v_cndmask_b32_e32 v162, v134, v47, vcc
	v_cmp_le_i32_e32 vcc, v38, v147
	v_add_u32_e32 v38, 0xffffff9a, v152
	v_exp_f32_e32 v47, v55
	v_cndmask_b32_e32 v63, v134, v63, vcc
	v_cmp_le_i32_e32 vcc, v38, v147
	v_add_u32_e32 v38, 0xffffffba, v152
	v_exp_f32_e32 v55, v59
	v_cndmask_b32_e32 v163, v134, v48, vcc
	v_cmp_le_i32_e32 vcc, v38, v147
	v_add_u32_e32 v38, 0xffffff9b, v152
	v_exp_f32_e32 v48, v155
	v_cndmask_b32_e32 v164, v134, v64, vcc
	v_cmp_le_i32_e32 vcc, v38, v147
	v_add_u32_e32 v38, 0xffffffbb, v152
	v_exp_f32_e32 v56, v159
	v_cndmask_b32_e32 v165, v134, v49, vcc
	v_cmp_le_i32_e32 vcc, v38, v147
	v_pk_add_f32 v[38:39], v[34:35], 0 op_sel_hi:[1,0]
	v_exp_f32_e32 v49, v156
	v_pk_add_f32 v[38:39], v[42:43], v[38:39]
	v_exp_f32_e32 v57, v160
	v_pk_add_f32 v[38:39], v[36:37], v[38:39]
	v_exp_f32_e32 v58, v60
	v_pk_add_f32 v[38:39], v[44:45], v[38:39]
	v_exp_f32_e32 v59, v61
	v_pk_add_f32 v[38:39], v[40:41], v[38:39]
	v_exp_f32_e32 v60, v161
	v_pk_add_f32 v[38:39], v[46:47], v[38:39]
	v_exp_f32_e32 v61, v162
	v_pk_add_f32 v[38:39], v[48:49], v[38:39]
	v_exp_f32_e32 v62, v62
	v_pk_add_f32 v[38:39], v[50:51], v[38:39]
	v_exp_f32_e32 v63, v63
	v_pk_add_f32 v[38:39], v[52:53], v[38:39]
	v_cndmask_b32_e32 v166, v134, v65, vcc
	v_pk_add_f32 v[38:39], v[54:55], v[38:39]
	v_exp_f32_e32 v64, v163
	v_pk_add_f32 v[38:39], v[56:57], v[38:39]
	v_exp_f32_e32 v65, v165
	v_pk_add_f32 v[38:39], v[58:59], v[38:39]
	v_exp_f32_e32 v152, v164
	v_exp_f32_e32 v153, v166
	v_pk_add_f32 v[38:39], v[60:61], v[38:39]
	v_cvt_pk_bf16_f32 v42, v42, v43
	v_pk_add_f32 v[38:39], v[62:63], v[38:39]
	v_cvt_pk_bf16_f32 v43, v44, v45
	v_pk_add_f32 v[38:39], v[64:65], v[38:39]
	v_cvt_pk_bf16_f32 v45, v50, v51
	v_pk_add_f32 v[38:39], v[152:153], v[38:39]
	ds_read_b64_tr_b16 v[50:51],v150 offset:0
	v_cvt_pk_bf16_f32 v44, v46, v47
	v_add_f32_e32 v38, v38, v39
	v_add_f32_e32 v154, v148, v38
	v_cvt_pk_bf16_f32 v38, v52, v53
	ds_read_b64_tr_b16 v[52:53],v150 offset:512
	v_cvt_pk_bf16_f32 v46, v54, v55
	ds_read_b64_tr_b16 v[54:55],v150 offset:1024
	v_cvt_pk_bf16_f32 v39, v56, v57
	ds_read_b64_tr_b16 v[56:57],v150 offset:1536
	v_cvt_pk_bf16_f32 v47, v58, v59
	ds_read_b64_tr_b16 v[58:59],v150 offset:2048
	v_cvt_pk_bf16_f32 v34, v34, v35
	v_cvt_pk_bf16_f32 v35, v36, v37
	v_cvt_pk_bf16_f32 v36, v40, v41
	v_cvt_pk_bf16_f32 v40, v60, v61
	ds_read_b64_tr_b16 v[60:61],v150 offset:2560
	v_cvt_pk_bf16_f32 v37, v48, v49
	v_cvt_pk_bf16_f32 v48, v62, v63
	ds_read_b64_tr_b16 v[62:63],v150 offset:3072
	v_cvt_pk_bf16_f32 v41, v64, v65
	ds_read_b64_tr_b16 v[64:65],v150 offset:3584
	s_waitcnt lgkmcnt(0)
	v_cvt_pk_bf16_f32 v49, v152, v153
	v_mfma_f32_32x32x16_bf16 v[2:17], v[34:37], v[50:53], v[2:17]
	ds_read_b64_tr_b16 v[50:51],v150 offset:4096
	ds_read_b64_tr_b16 v[52:53],v150 offset:4608
	v_mfma_f32_32x32x16_bf16 v[2:17], v[38:41], v[54:57], v[2:17]
	ds_read_b64_tr_b16 v[54:55],v150 offset:5120
	ds_read_b64_tr_b16 v[56:57],v150 offset:5632
	v_mfma_f32_32x32x16_bf16 v[2:17], v[42:45], v[58:61], v[2:17]
	ds_read_b64_tr_b16 v[58:59],v150 offset:6144
	ds_read_b64_tr_b16 v[60:61],v150 offset:6656
	ds_read_b64_tr_b16 v[156:157],v150 offset:7168
	ds_read_b64_tr_b16 v[158:159],v150 offset:7680
	s_waitcnt lgkmcnt(0)
	v_mfma_f32_32x32x16_bf16 v[2:17], v[46:49], v[62:65], v[2:17]
	v_mfma_f32_32x32x16_bf16 v[18:33], v[34:37], v[50:53], v[18:33]
	v_mfma_f32_32x32x16_bf16 v[18:33], v[38:41], v[54:57], v[18:33]
	v_mfma_f32_32x32x16_bf16 v[18:33], v[42:45], v[58:61], v[18:33]
	v_mfma_f32_32x32x16_bf16 v[18:33], v[46:49], v[156:159], v[18:33]

; #define LAS __attribute__((address_space(3)))
; template <bool BAND>
; __device__ __forceinline__ void tile_body(f32x16* o, float& l_reg, const bf16x8* qr, const LAS unsigned char* kbs, const LAS float* wb, int vb, float ci, int hi, int keybase, int qabs) {
;     ...
; #pragma unroll
;     for (int g4 = 0; g4 < 4; ++g4) {
;         const f32x4 ba = *(const LAS f32x4*)(wb + 8 * g4 + 4 * hi) + ci, bb = *(const LAS f32x4*)(wb + 32 + 8 * g4 + 4 * hi) + ci;
; #pragma unroll
;         for (int e = 0; e < 4; ++e) { p0[4 * g4 + e] = ba[e]; p1[4 * g4 + e] = bb[e]; }
;     }
; #pragma unroll
;     for (int d0 = 0; d0 < 4; ++d0) {
;         const bf16x8 b0 = *(const LAS bf16x8*)(kbs + d0 * 2048), b1 = *(const LAS bf16x8*)(kbs + d0 * 2048 + 512);
;         p0 = __builtin_amdgcn_mfma_f32_32x32x16_bf16(b0, qr[d0], p0, 0, 0, 0); p1 = __builtin_amdgcn_mfma_f32_32x32x16_bf16(b1, qr[d0], p1, 0, 0, 0); }
;     if (BAND) {
; #pragma unroll
;         for (int r = 0; r < 16; ++r) { const int key = keybase + 8 * (r >> 2) + (r & 3); if (key > qabs) p0[r] = -INFINITY; if (key + 32 > qabs) p1[r] = -INFINITY; }
.LBB0_819:
	s_andn2_b64 vcc, exec, s[68:69]
	s_cbranch_vccnz .LBB0_774
	s_and_b64 vcc, exec, s[98:99]
	s_cbranch_vccnz .LBB0_774
	s_add_i32 s28, s75, 0xffffff40
	s_cmp_gt_i32 s28, s73
	s_cbranch_scc1 .LBB0_774
	s_add_i32 s68, s48, -2
	s_cmp_lt_i32 s68, s72
	v_add_u32_e32 v0, s77, v144
	s_mov_b64 s[68:69], -1
	v_add_u32_e32 v149, s77, v145
	v_lshl_add_u32 v150, v142, 2, s76
	s_cbranch_scc1 .LBB0_823
	ds_read_b128 v[34:37], v150 offset:32768
	ds_read_b128 v[38:41], v150 offset:32800
	ds_read_b128 v[42:45], v150 offset:32832
	ds_read_b128 v[46:49], v150 offset:32864
	ds_read_b128 v[50:53], v150 offset:32896
	ds_read_b128 v[54:57], v150 offset:32928
	ds_read_b128 v[58:61], v150 offset:32960
	ds_read_b128 v[62:65], v150 offset:32992
	ds_read_b128 v[152:155], v149
	ds_read_b128 v[156:159], v149 offset:512
	s_waitcnt lgkmcnt(4)
	ds_read_b128 v[210:213], v149 offset:2048
	ds_read_b128 v[214:217], v149 offset:2560
	ds_read_b128 v[218:221], v149 offset:4096
	ds_read_b128 v[222:225], v149 offset:4608
	ds_read_b128 v[226:229], v149 offset:6656
	ds_read_b128 v[230:233], v149 offset:6144
	v_pk_add_f32 v[56:57], v[118:119], v[56:57]
	s_waitcnt lgkmcnt(9)
	v_pk_add_f32 v[60:61], v[122:123], v[60:61]
	s_waitcnt lgkmcnt(8)
	v_pk_add_f32 v[64:65], v[126:127], v[64:65]
	v_pk_add_f32 v[52:53], v[114:115], v[52:53]
	v_pk_add_f32 v[62:63], v[124:125], v[62:63]
	v_pk_add_f32 v[58:59], v[120:121], v[58:59]
	v_pk_add_f32 v[54:55], v[116:117], v[54:55]
	v_pk_add_f32 v[50:51], v[112:113], v[50:51]
	v_pk_add_f32 v[48:49], v[126:127], v[48:49]
	v_pk_add_f32 v[44:45], v[122:123], v[44:45]
	v_pk_add_f32 v[40:41], v[118:119], v[40:41]
	v_pk_add_f32 v[36:37], v[114:115], v[36:37]
	v_pk_add_f32 v[46:47], v[124:125], v[46:47]
	v_pk_add_f32 v[42:43], v[120:121], v[42:43]
	v_pk_add_f32 v[38:39], v[116:117], v[38:39]
	v_pk_add_f32 v[34:35], v[112:113], v[34:35]
	s_waitcnt lgkmcnt(6)
	v_mfma_f32_32x32x16_bf16 v[50:65], v[156:159], v[94:97], v[50:65]
	v_mfma_f32_32x32x16_bf16 v[34:49], v[152:155], v[94:97], v[34:49]
	s_waitcnt lgkmcnt(4)
	v_mfma_f32_32x32x16_bf16 v[50:65], v[214:217], v[98:101], v[50:65]
	v_mfma_f32_32x32x16_bf16 v[34:49], v[210:213], v[98:101], v[34:49]
	s_waitcnt lgkmcnt(2)
	v_mfma_f32_32x32x16_bf16 v[50:65], v[222:225], v[102:105], v[50:65]
	v_mfma_f32_32x32x16_bf16 v[34:49], v[218:221], v[102:105], v[34:49]
	s_waitcnt lgkmcnt(1)
	v_mfma_f32_32x32x16_bf16 v[50:65], v[226:229], v[90:93], v[50:65]
	v_add_u32_e32 v152, s75, v142
	v_add_u32_e32 v154, 0xffffff60, v152
	v_add_u32_e32 v153, 0xffffff40, v152
	v_cmp_le_i32_e32 vcc, v154, v147
	s_waitcnt lgkmcnt(0)
	v_mfma_f32_32x32x16_bf16 v[34:49], v[230:233], v[90:93], v[34:49]
	s_nop 5
	v_cndmask_b32_e32 v50, v134, v50, vcc
	v_cmp_lt_i32_e32 vcc, v153, v147
	s_nop 3
	v_cndmask_b32_e32 v35, v134, v35, vcc
	v_cmp_le_i32_e32 vcc, v153, v147
	v_add_u32_e32 v153, 0xffffff61, v152
	v_exp_f32_e32 v35, v35
	v_cndmask_b32_e32 v34, v134, v34, vcc
	v_cmp_le_i32_e32 vcc, v153, v147
	v_add_u32_e32 v153, 0xffffff42, v152
	v_exp_f32_e32 v34, v34
	v_cndmask_b32_e32 v51, v134, v51, vcc
	v_cmp_le_i32_e32 vcc, v153, v147
	s_nop 1
	v_cndmask_b32_e32 v153, v134, v36, vcc
	v_add_u32_e32 v36, 0xffffff62, v152
	v_cmp_le_i32_e32 vcc, v36, v147
	v_add_u32_e32 v36, 0xffffff43, v152
	s_nop 0
	v_cndmask_b32_e32 v52, v134, v52, vcc
	v_cmp_le_i32_e32 vcc, v36, v147
	v_add_u32_e32 v36, 0xffffff63, v152
	s_nop 0
	v_cndmask_b32_e32 v154, v134, v37, vcc
	v_cmp_le_i32_e32 vcc, v36, v147
	v_add_u32_e32 v36, 0xffffff48, v152
	v_exp_f32_e32 v37, v51
	v_cndmask_b32_e32 v53, v134, v53, vcc
	v_cmp_le_i32_e32 vcc, v36, v147
	v_add_u32_e32 v36, 0xffffff68, v152
	s_nop 0
	v_cndmask_b32_e32 v155, v134, v38, vcc
	v_cmp_le_i32_e32 vcc, v36, v147
	v_add_u32_e32 v36, 0xffffff49, v152
	v_exp_f32_e32 v38, v153
	v_cndmask_b32_e32 v54, v134, v54, vcc
	v_cmp_le_i32_e32 vcc, v36, v147
	v_add_u32_e32 v36, 0xffffff69, v152
	s_nop 0
	v_cndmask_b32_e32 v156, v134, v39, vcc
	v_cmp_le_i32_e32 vcc, v36, v147
	v_add_u32_e32 v36, 0xffffff4a, v152
	v_exp_f32_e32 v39, v154
	v_cndmask_b32_e32 v55, v134, v55, vcc
	v_cmp_le_i32_e32 vcc, v36, v147
	v_add_u32_e32 v36, 0xffffff6a, v152
	v_cvt_pk_bf16_f32 v154, v34, v35
	v_cndmask_b32_e32 v157, v134, v40, vcc
	v_cmp_le_i32_e32 vcc, v36, v147
	v_add_u32_e32 v36, 0xffffff4b, v152
	v_exp_f32_e32 v40, v52
	v_cndmask_b32_e32 v56, v134, v56, vcc
	v_cmp_le_i32_e32 vcc, v36, v147
	v_add_u32_e32 v36, 0xffffff6b, v152
	s_nop 0
	v_cndmask_b32_e32 v158, v134, v41, vcc
	v_cmp_le_i32_e32 vcc, v36, v147
	v_add_u32_e32 v36, 0xffffff50, v152
	v_exp_f32_e32 v41, v53
	v_cndmask_b32_e32 v57, v134, v57, vcc
	v_cmp_le_i32_e32 vcc, v36, v147
	v_add_u32_e32 v36, 0xffffff70, v152
	v_exp_f32_e32 v51, v57
	v_cndmask_b32_e32 v159, v134, v42, vcc
	v_cmp_le_i32_e32 vcc, v36, v147
	v_add_u32_e32 v36, 0xffffff51, v152
	v_exp_f32_e32 v52, v159
	v_cndmask_b32_e32 v58, v134, v58, vcc
	v_cmp_le_i32_e32 vcc, v36, v147
	v_add_u32_e32 v36, 0xffffff71, v152
	s_nop 0
	v_cndmask_b32_e32 v160, v134, v43, vcc
	v_cmp_le_i32_e32 vcc, v36, v147
	v_add_u32_e32 v36, 0xffffff52, v152
	v_pk_add_f32 v[42:43], v[34:35], 0 op_sel_hi:[1,0]
	v_cndmask_b32_e32 v59, v134, v59, vcc
	v_cmp_le_i32_e32 vcc, v36, v147
	v_add_u32_e32 v36, 0xffffff72, v152
	v_exp_f32_e32 v53, v160
	v_cndmask_b32_e32 v161, v134, v44, vcc
	v_cmp_le_i32_e32 vcc, v36, v147
	v_add_u32_e32 v36, 0xffffff53, v152
	v_exp_f32_e32 v44, v155
	v_cndmask_b32_e32 v60, v134, v60, vcc
	v_cmp_le_i32_e32 vcc, v36, v147
	v_add_u32_e32 v36, 0xffffff73, v152
	v_cvt_pk_bf16_f32 v155, v38, v39
	v_cndmask_b32_e32 v162, v134, v45, vcc
	v_cmp_le_i32_e32 vcc, v36, v147
	v_add_u32_e32 v36, 0xffffff58, v152
	v_exp_f32_e32 v45, v156
; __device__ __forceinline__ void pv(f32x16* o, int vb, bf16x8 pa0, bf16x8 pa1, bf16x8 pa2, bf16x8 pa3) {
; #pragma unroll
;     for (int d0 = 0; d0 < 2; ++d0) { s16x4 lo[4], hi[4];
; #pragma unroll
;         for (int ks = 0; ks < 4; ++ks) {
;             asm volatile("ds_read_b64_tr_b16 %0,%1 offset:%c2" : "=&v"(lo[ks]) : "v"(vb), "i"(d0 * 4096 + ks * 1024) : "memory");
;             asm volatile("ds_read_b64_tr_b16 %0,%1 offset:%c2" : "=&v"(hi[ks]) : "v"(vb), "i"(d0 * 4096 + ks * 1024 + 512) : "memory"); }
;         asm volatile("s_waitcnt lgkmcnt(0)" ::: "memory"); __builtin_amdgcn_sched_barrier(0);
;     ...
;         o[d0] = __builtin_amdgcn_mfma_f32_32x32x16_bf16(pa0, PK(0), o[d0], 0, 0, 0);
;         o[d0] = __builtin_amdgcn_mfma_f32_32x32x16_bf16(pa1, PK(1), o[d0], 0, 0, 0);
;         o[d0] = __builtin_amdgcn_mfma_f32_32x32x16_bf16(pa2, PK(2), o[d0], 0, 0, 0);
;         o[d0] = __builtin_amdgcn_mfma_f32_32x32x16_bf16(pa3, PK(3), o[d0], 0, 0, 0);
; template <bool BAND>
; __device__ __forceinline__ void tile_body(f32x16* o, float& l_reg, const bf16x8* qr, const LAS unsigned char* kbs, const LAS float* wb, int vb, float ci, int hi, int keybase, int qabs) {
;     ...
;         for (int r = 0; r < 16; ++r) { const int key = keybase + 8 * (r >> 2) + (r & 3); if (key > qabs) p0[r] = -INFINITY; if (key + 32 > qabs) p1[r] = -INFINITY; }
;     }
;     f32x2 s2 = {0.f, 0.f};
; #pragma unroll
;     for (int r = 0; r < 16; r += 2) {
;         p0[r] = __builtin_amdgcn_exp2f(p0[r]); p0[r + 1] = __builtin_amdgcn_exp2f(p0[r + 1]); p1[r] = __builtin_amdgcn_exp2f(p1[r]); p1[r + 1] = __builtin_amdgcn_exp2f(p1[r + 1]);
;         s2 += (f32x2){p0[r], p0[r + 1]}; s2 += (f32x2){p1[r], p1[r + 1]}; }
;     l_reg += s2.x + s2.y;
;     u32x4 pw0, pw1, pw2, pw3;
;     pw0 = (u32x4){cvtpk(p0[0], p0[1]), cvtpk(p0[2], p0[3]), cvtpk(p0[4], p0[5]), cvtpk(p0[6], p0[7])};
;     pw1 = (u32x4){cvtpk(p0[8], p0[9]), cvtpk(p0[10], p0[11]), cvtpk(p0[12], p0[13]), cvtpk(p0[14], p0[15])};
;     pw2 = (u32x4){cvtpk(p1[0], p1[1]), cvtpk(p1[2], p1[3]), cvtpk(p1[4], p1[5]), cvtpk(p1[6], p1[7])};
;     pw3 = (u32x4){cvtpk(p1[8], p1[9]), cvtpk(p1[10], p1[11]), cvtpk(p1[12], p1[13]), cvtpk(p1[14], p1[15])};
;     pv(o, vb, __builtin_bit_cast(bf16x8, pw0), __builtin_bit_cast(bf16x8, pw1), __builtin_bit_cast(bf16x8, pw2), __builtin_bit_cast(bf16x8, pw3));
	v_cndmask_b32_e32 v61, v134, v61, vcc
	v_cmp_le_i32_e32 vcc, v36, v147
	v_add_u32_e32 v36, 0xffffff78, v152
	v_exp_f32_e32 v57, v162
	v_cndmask_b32_e32 v163, v134, v46, vcc
	v_cmp_le_i32_e32 vcc, v36, v147
	v_add_u32_e32 v36, 0xffffff59, v152
	v_exp_f32_e32 v46, v54
	v_cndmask_b32_e32 v62, v134, v62, vcc
	v_cmp_le_i32_e32 vcc, v36, v147
	v_add_u32_e32 v36, 0xffffff79, v152
	v_exp_f32_e32 v54, v58
	v_cndmask_b32_e32 v164, v134, v47, vcc
	v_cmp_le_i32_e32 vcc, v36, v147
	v_add_u32_e32 v36, 0xffffff5a, v152
	v_exp_f32_e32 v47, v55
	v_cndmask_b32_e32 v63, v134, v63, vcc
	v_cmp_le_i32_e32 vcc, v36, v147
	v_add_u32_e32 v36, 0xffffff7a, v152
	v_exp_f32_e32 v55, v59
	v_cndmask_b32_e32 v165, v134, v48, vcc
	v_cmp_le_i32_e32 vcc, v36, v147
	v_add_u32_e32 v36, 0xffffff5b, v152
	v_exp_f32_e32 v48, v157
	v_cndmask_b32_e32 v166, v134, v64, vcc
	v_cmp_le_i32_e32 vcc, v36, v147
	v_add_u32_e32 v36, 0xffffff7b, v152
	v_exp_f32_e32 v58, v60
	v_cndmask_b32_e32 v167, v134, v49, vcc
	v_cmp_le_i32_e32 vcc, v36, v147
	v_exp_f32_e32 v36, v50
	v_exp_f32_e32 v49, v158
	v_exp_f32_e32 v50, v56
	v_exp_f32_e32 v56, v161
	v_pk_add_f32 v[42:43], v[36:37], v[42:43]
	v_exp_f32_e32 v59, v61
	v_pk_add_f32 v[42:43], v[38:39], v[42:43]
	v_exp_f32_e32 v64, v165
	v_pk_add_f32 v[42:43], v[40:41], v[42:43]
	v_cvt_pk_bf16_f32 v165, v50, v51
	v_pk_add_f32 v[42:43], v[44:45], v[42:43]
	v_exp_f32_e32 v60, v163
	v_pk_add_f32 v[42:43], v[46:47], v[42:43]
	v_exp_f32_e32 v61, v164
	v_pk_add_f32 v[42:43], v[48:49], v[42:43]
	v_cvt_pk_bf16_f32 v158, v52, v53
	v_pk_add_f32 v[42:43], v[50:51], v[42:43]
	ds_read_b64_tr_b16 v[50:51],v0 offset:0
	v_exp_f32_e32 v62, v62
	v_pk_add_f32 v[42:43], v[52:53], v[42:43]
	ds_read_b64_tr_b16 v[52:53],v0 offset:512
	v_exp_f32_e32 v63, v63
	v_pk_add_f32 v[42:43], v[54:55], v[42:43]
	v_exp_f32_e32 v170, v166
	v_cvt_pk_bf16_f32 v166, v54, v55
	ds_read_b64_tr_b16 v[54:55],v0 offset:1024
	v_cndmask_b32_e32 v152, v134, v65, vcc
	v_pk_add_f32 v[42:43], v[56:57], v[42:43]
	v_exp_f32_e32 v65, v167
	v_cvt_pk_bf16_f32 v159, v56, v57
	ds_read_b64_tr_b16 v[56:57],v0 offset:1536
	v_pk_add_f32 v[42:43], v[58:59], v[42:43]
	v_exp_f32_e32 v171, v152
	v_cvt_pk_bf16_f32 v167, v58, v59
	ds_read_b64_tr_b16 v[58:59],v0 offset:2048
	v_pk_add_f32 v[42:43], v[60:61], v[42:43]
	v_cvt_pk_bf16_f32 v160, v60, v61
	ds_read_b64_tr_b16 v[60:61],v0 offset:2560
	v_pk_add_f32 v[42:43], v[62:63], v[42:43]
	v_cvt_pk_bf16_f32 v168, v62, v63
	ds_read_b64_tr_b16 v[62:63],v0 offset:3072
	v_pk_add_f32 v[42:43], v[64:65], v[42:43]
	v_cvt_pk_bf16_f32 v161, v64, v65
	ds_read_b64_tr_b16 v[64:65],v0 offset:3584
	v_pk_add_f32 v[42:43], v[170:171], v[42:43]
	s_waitcnt lgkmcnt(0)
	v_cvt_pk_bf16_f32 v156, v44, v45
	v_add_f32_e32 v42, v42, v43
	v_add_f32_e32 v152, v148, v42
	v_cvt_pk_bf16_f32 v157, v48, v49
	v_cvt_pk_bf16_f32 v162, v36, v37
	v_cvt_pk_bf16_f32 v163, v40, v41
	v_cvt_pk_bf16_f32 v164, v46, v47
	v_cvt_pk_bf16_f32 v169, v170, v171
	v_mfma_f32_32x32x16_bf16 v[2:17], v[154:157], v[50:53], v[2:17]
	ds_read_b64_tr_b16 v[170:171],v0 offset:4096
	ds_read_b64_tr_b16 v[172:173],v0 offset:4608
	ds_read_b64_tr_b16 v[174:175],v0 offset:5120
	ds_read_b64_tr_b16 v[176:177],v0 offset:5632
	ds_read_b64_tr_b16 v[178:179],v0 offset:6144
	ds_read_b64_tr_b16 v[180:181],v0 offset:6656
	ds_read_b64_tr_b16 v[182:183],v0 offset:7168
	v_mfma_f32_32x32x16_bf16 v[2:17], v[158:161], v[54:57], v[2:17]
	ds_read_b64_tr_b16 v[184:185],v0 offset:7680
	s_waitcnt lgkmcnt(0)
	v_mfma_f32_32x32x16_bf16 v[2:17], v[162:165], v[58:61], v[2:17]
	v_mfma_f32_32x32x16_bf16 v[2:17], v[166:169], v[62:65], v[2:17]
	v_mfma_f32_32x32x16_bf16 v[18:33], v[154:157], v[170:173], v[18:33]
	s_mov_b64 s[68:69], 0
	v_mfma_f32_32x32x16_bf16 v[18:33], v[158:161], v[174:177], v[18:33]
	v_mfma_f32_32x32x16_bf16 v[18:33], v[162:165], v[178:181], v[18:33]
	v_mfma_f32_32x32x16_bf16 v[18:33], v[166:169], v[182:185], v[18:33]
; #define LAS __attribute__((address_space(3)))
; __device__ __forceinline__ unsigned cvtpk(float lo, float hi) { typedef __bf16 bf16x2_t __attribute__((ext_vector_type(2))); f32x2 v = {lo, hi}; bf16x2_t b = __builtin_convertvector(v, bf16x2_t); return __builtin_bit_cast(unsigned, b); }
; template <bool BAND>
; __device__ __forceinline__ void tile_body(f32x16* o, float& l_reg, const bf16x8* qr, const LAS unsigned char* kbs, const LAS float* wb, int vb, float ci, int hi, int keybase, int qabs) {
;     f32x16 p0, p1;
; #pragma unroll
;     for (int g4 = 0; g4 < 4; ++g4) {
;         const f32x4 ba = *(const LAS f32x4*)(wb + 8 * g4 + 4 * hi) + ci, bb = *(const LAS f32x4*)(wb + 32 + 8 * g4 + 4 * hi) + ci;
; #pragma unroll
;         for (int e = 0; e < 4; ++e) { p0[4 * g4 + e] = ba[e]; p1[4 * g4 + e] = bb[e]; }
;     }
; #pragma unroll
;     for (int d0 = 0; d0 < 4; ++d0) {
;         const bf16x8 b0 = *(const LAS bf16x8*)(kbs + d0 * 2048), b1 = *(const LAS bf16x8*)(kbs + d0 * 2048 + 512);
;         p0 = __builtin_amdgcn_mfma_f32_32x32x16_bf16(b0, qr[d0], p0, 0, 0, 0); p1 = __builtin_amdgcn_mfma_f32_32x32x16_bf16(b1, qr[d0], p1, 0, 0, 0); }
;     if (BAND) {
; #pragma unroll
;         for (int r = 0; r < 16; ++r) { const int key = keybase + 8 * (r >> 2) + (r & 3); if (key > qabs) p0[r] = -INFINITY; if (key + 32 > qabs) p1[r] = -INFINITY; }
;     }
;     f32x2 s2 = {0.f, 0.f};
; #pragma unroll
;     for (int r = 0; r < 16; r += 2) {
;         p0[r] = __builtin_amdgcn_exp2f(p0[r]); p0[r + 1] = __builtin_amdgcn_exp2f(p0[r + 1]); p1[r] = __builtin_amdgcn_exp2f(p1[r]); p1[r + 1] = __builtin_amdgcn_exp2f(p1[r + 1]);
;         s2 += (f32x2){p0[r], p0[r + 1]}; s2 += (f32x2){p1[r], p1[r + 1]}; }
;     l_reg += s2.x + s2.y;
;     u32x4 pw0, pw1, pw2, pw3;
;     pw0 = (u32x4){cvtpk(p0[0], p0[1]), cvtpk(p0[2], p0[3]), cvtpk(p0[4], p0[5]), cvtpk(p0[6], p0[7])};
;     pw1 = (u32x4){cvtpk(p0[8], p0[9]), cvtpk(p0[10], p0[11]), cvtpk(p0[12], p0[13]), cvtpk(p0[14], p0[15])};
;     pw2 = (u32x4){cvtpk(p1[0], p1[1]), cvtpk(p1[2], p1[3]), cvtpk(p1[4], p1[5]), cvtpk(p1[6], p1[7])};
;     pw3 = (u32x4){cvtpk(p1[8], p1[9]), cvtpk(p1[10], p1[11]), cvtpk(p1[12], p1[13]), cvtpk(p1[14], p1[15])};
;     pv(o, vb, __builtin_bit_cast(bf16x8, pw0), __builtin_bit_cast(bf16x8, pw1), __builtin_bit_cast(bf16x8, pw2), __builtin_bit_cast(bf16x8, pw3));
.LBB0_823:
	s_andn2_b64 vcc, exec, s[68:69]
	s_cbranch_vccnz .Lmy_attjoin_C
	s_nop 4
	ds_read_b128 v[34:37], v150 offset:32768
	ds_read_b128 v[38:41], v150 offset:32800
	ds_read_b128 v[42:45], v150 offset:32832
	ds_read_b128 v[46:49], v150 offset:32864
	s_nop 0
	ds_read_b128 v[50:53], v150 offset:32896
	ds_read_b128 v[54:57], v150 offset:32928
	ds_read_b128 v[58:61], v150 offset:32960
	ds_read_b128 v[62:65], v150 offset:32992
	ds_read_b128 v[152:155], v149
	ds_read_b128 v[156:159], v149 offset:512
	s_waitcnt lgkmcnt(6)
	ds_read_b128 v[210:213], v149 offset:2048
	ds_read_b128 v[214:217], v149 offset:2560
	ds_read_b128 v[218:221], v149 offset:4096
	ds_read_b128 v[222:225], v149 offset:4608
	ds_read_b128 v[226:229], v149 offset:6144
	ds_read_b128 v[230:233], v149 offset:6656
	v_pk_add_f32 v[48:49], v[126:127], v[48:49]
	v_pk_add_f32 v[44:45], v[122:123], v[44:45]
	v_pk_add_f32 v[40:41], v[118:119], v[40:41]
	v_pk_add_f32 v[36:37], v[114:115], v[36:37]
	v_pk_add_f32 v[46:47], v[124:125], v[46:47]
	v_pk_add_f32 v[42:43], v[120:121], v[42:43]
	v_pk_add_f32 v[38:39], v[116:117], v[38:39]
	v_pk_add_f32 v[34:35], v[112:113], v[34:35]
	s_waitcnt lgkmcnt(8)
	v_pk_add_f32 v[64:65], v[126:127], v[64:65]
	v_pk_add_f32 v[60:61], v[122:123], v[60:61]
	s_waitcnt lgkmcnt(7)
	v_mfma_f32_32x32x16_bf16 v[34:49], v[152:155], v[94:97], v[34:49]
	v_add_f32_e64 v56, v118, v56
	v_add_f32_e64 v57, v119, v57
	v_add_f32_e64 v52, v114, v52
	v_add_f32_e64 v53, v115, v53
	v_add_f32_e64 v62, v124, v62
	v_add_f32_e64 v63, v125, v63
	v_pk_add_f32 v[58:59], v[120:121], v[58:59]
	v_pk_add_f32 v[54:55], v[116:117], v[54:55]
	v_pk_add_f32 v[50:51], v[112:113], v[50:51]
	s_waitcnt lgkmcnt(6)
	s_nop 0
	v_mfma_f32_32x32x16_bf16 v[50:65], v[156:159], v[94:97], v[50:65]
	s_waitcnt lgkmcnt(5)
	v_mfma_f32_32x32x16_bf16 v[34:49], v[210:213], v[98:101], v[34:49]
	s_waitcnt lgkmcnt(4)
	v_mfma_f32_32x32x16_bf16 v[50:65], v[214:217], v[98:101], v[50:65]
	s_waitcnt lgkmcnt(3)
	v_mfma_f32_32x32x16_bf16 v[34:49], v[218:221], v[102:105], v[34:49]
	s_waitcnt lgkmcnt(2)
	v_mfma_f32_32x32x16_bf16 v[50:65], v[222:225], v[102:105], v[50:65]
	s_waitcnt lgkmcnt(1)
	v_mfma_f32_32x32x16_bf16 v[34:49], v[226:229], v[90:93], v[34:49]
	s_waitcnt lgkmcnt(0)
	v_mfma_f32_32x32x16_bf16 v[50:65], v[230:233], v[90:93], v[50:65]
	s_nop 9
	v_exp_f32_e32 v34, v34
	v_exp_f32_e32 v35, v35
	v_exp_f32_e32 v36, v36
	v_exp_f32_e32 v37, v37
	v_exp_f32_e32 v38, v38
	v_pk_add_f32 v[152:153], v[34:35], 0 op_sel_hi:[1,0]
	v_exp_f32_e32 v39, v39
	v_exp_f32_e32 v50, v50
	v_exp_f32_e32 v51, v51
	v_exp_f32_e32 v52, v52
	v_exp_f32_e32 v53, v53
	v_exp_f32_e32 v54, v54
	v_pk_add_f32 v[152:153], v[50:51], v[152:153]
	v_exp_f32_e32 v55, v55
	v_pk_add_f32 v[152:153], v[36:37], v[152:153]
	v_exp_f32_e32 v40, v40
	v_exp_f32_e32 v41, v41
	v_pk_add_f32 v[152:153], v[52:53], v[152:153]
	v_exp_f32_e32 v56, v56
	v_exp_f32_e32 v57, v57
	v_pk_add_f32 v[152:153], v[38:39], v[152:153]
	v_exp_f32_e32 v42, v42
	v_exp_f32_e32 v43, v43
	v_pk_add_f32 v[152:153], v[54:55], v[152:153]
	v_exp_f32_e32 v58, v58
	v_exp_f32_e32 v59, v59
	v_pk_add_f32 v[152:153], v[40:41], v[152:153]
	v_exp_f32_e32 v44, v44
	v_exp_f32_e32 v45, v45
	v_pk_add_f32 v[152:153], v[56:57], v[152:153]
	v_exp_f32_e32 v60, v60
	v_exp_f32_e32 v61, v61
	v_pk_add_f32 v[152:153], v[42:43], v[152:153]
	v_exp_f32_e32 v46, v46
	v_exp_f32_e32 v47, v47
	v_cvt_pk_bf16_f32 v34, v34, v35
	v_cvt_pk_bf16_f32 v35, v36, v37
	v_cvt_pk_bf16_f32 v36, v38, v39
	v_cvt_pk_bf16_f32 v38, v42, v43
	v_cvt_pk_bf16_f32 v42, v50, v51
	ds_read_b64_tr_b16 v[50:51],v0 offset:0
	v_pk_add_f32 v[152:153], v[58:59], v[152:153]
	v_exp_f32_e32 v62, v62
	v_exp_f32_e32 v63, v63
	v_cvt_pk_bf16_f32 v43, v52, v53
	ds_read_b64_tr_b16 v[52:53],v0 offset:512
	v_pk_add_f32 v[152:153], v[44:45], v[152:153]
	v_exp_f32_e32 v48, v48
	v_exp_f32_e32 v49, v49
	v_cvt_pk_bf16_f32 v39, v44, v45
	v_cvt_pk_bf16_f32 v44, v54, v55
	ds_read_b64_tr_b16 v[54:55],v0 offset:1024
	v_pk_add_f32 v[152:153], v[60:61], v[152:153]
	v_exp_f32_e32 v64, v64
	v_exp_f32_e32 v65, v65
	v_cvt_pk_bf16_f32 v45, v56, v57
	ds_read_b64_tr_b16 v[56:57],v0 offset:1536
	v_pk_add_f32 v[152:153], v[46:47], v[152:153]
	v_cvt_pk_bf16_f32 v37, v40, v41
	v_cvt_pk_bf16_f32 v40, v46, v47
	v_cvt_pk_bf16_f32 v46, v58, v59
	ds_read_b64_tr_b16 v[58:59],v0 offset:2048
	v_pk_add_f32 v[152:153], v[62:63], v[152:153]
	v_cvt_pk_bf16_f32 v47, v60, v61
	ds_read_b64_tr_b16 v[60:61],v0 offset:2560
	v_pk_add_f32 v[152:153], v[48:49], v[152:153]
	v_cvt_pk_bf16_f32 v41, v48, v49
	v_cvt_pk_bf16_f32 v48, v62, v63
	ds_read_b64_tr_b16 v[62:63],v0 offset:3072
	v_pk_add_f32 v[152:153], v[64:65], v[152:153]
	v_cvt_pk_bf16_f32 v49, v64, v65
	ds_read_b64_tr_b16 v[64:65],v0 offset:3584
	s_waitcnt lgkmcnt(0)
	v_add_f32_e32 v149, v152, v153
	v_add_f32_e32 v152, v148, v149
	v_mfma_f32_32x32x16_bf16 v[2:17], v[34:37], v[50:53], v[2:17]
	ds_read_b64_tr_b16 v[50:51],v0 offset:4096
	ds_read_b64_tr_b16 v[52:53],v0 offset:4608
	v_mfma_f32_32x32x16_bf16 v[2:17], v[38:41], v[54:57], v[2:17]
	ds_read_b64_tr_b16 v[54:55],v0 offset:5120
	ds_read_b64_tr_b16 v[56:57],v0 offset:5632
	v_mfma_f32_32x32x16_bf16 v[2:17], v[42:45], v[58:61], v[2:17]
	ds_read_b64_tr_b16 v[58:59],v0 offset:6144
	ds_read_b64_tr_b16 v[60:61],v0 offset:6656
	ds_read_b64_tr_b16 v[154:155],v0 offset:7168
	ds_read_b64_tr_b16 v[156:157],v0 offset:7680
	s_waitcnt lgkmcnt(0)
	v_mfma_f32_32x32x16_bf16 v[2:17], v[46:49], v[62:65], v[2:17]
	v_mfma_f32_32x32x16_bf16 v[18:33], v[34:37], v[50:53], v[18:33]
	v_mfma_f32_32x32x16_bf16 v[18:33], v[38:41], v[54:57], v[18:33]
	v_mfma_f32_32x32x16_bf16 v[18:33], v[42:45], v[58:61], v[18:33]
	v_mfma_f32_32x32x16_bf16 v[18:33], v[46:49], v[154:157], v[18:33]
	s_branch .Lmy_attjoin_C
